# v19 with the GEMM K-loop LDS-DMA issue moved into the second (fresh-stage) MFMA half of each iteration
# baseline (speedup 1.0000x reference)
.Lgsk0_loop:
	s_add_i32 s9, s8, 0xfffe8000
	s_and_b32 s10, s8, 0x18000
	s_waitcnt vmcnt(8) lgkmcnt(0)
	s_barrier
	s_and_b32 s9, s9, 0x18000
	s_add_i32 s10, s7, s10
	v_add_u32_e32 v112, s9, v135
	v_or_b32_e32 v139, s9, v137
	s_add_i32 s18, s10, 0x400
	s_add_i32 s11, s10, 0x800
	s_add_i32 s9, s10, 0xc00
	s_add_i32 s8, s8, 0x8000
	s_cmp_eq_u32 s8, 0x100000
	ds_read_b128 v[186:189], v112
	ds_read_b128 v[190:193], v112 offset:1024
	ds_read_b128 v[194:197], v112 offset:2048
	ds_read_b128 v[198:201], v112 offset:3072
	v_mfma_f32_16x16x32_bf16 v[60:63], v[158:161], v[232:235], v[60:63]
	v_mfma_f32_16x16x32_bf16 v[44:47], v[158:161], v[236:239], v[44:47]
	v_mfma_f32_16x16x32_bf16 v[28:31], v[158:161], v[240:243], v[28:31]
	v_mfma_f32_16x16x32_bf16 v[12:15], v[158:161], v[244:247], v[12:15]
	v_mfma_f32_16x16x32_bf16 v[56:59], v[162:165], v[232:235], v[56:59]
	ds_read_b128 v[158:161], v139
	v_mfma_f32_16x16x32_bf16 v[40:43], v[162:165], v[236:239], v[40:43]
	v_mfma_f32_16x16x32_bf16 v[24:27], v[162:165], v[240:243], v[24:27]
	v_mfma_f32_16x16x32_bf16 v[8:11], v[162:165], v[244:247], v[8:11]
	v_mfma_f32_16x16x32_bf16 v[52:55], v[166:169], v[232:235], v[52:55]
	ds_read_b128 v[162:165], v139 offset:1024
	v_mfma_f32_16x16x32_bf16 v[36:39], v[166:169], v[236:239], v[36:39]
	v_mfma_f32_16x16x32_bf16 v[20:23], v[166:169], v[240:243], v[20:23]
	v_mfma_f32_16x16x32_bf16 v[4:7], v[166:169], v[244:247], v[4:7]
	v_mfma_f32_16x16x32_bf16 v[48:51], v[182:185], v[232:235], v[48:51]
	ds_read_b128 v[166:169], v139 offset:2048
	v_mfma_f32_16x16x32_bf16 v[32:35], v[182:185], v[236:239], v[32:35]
	v_mfma_f32_16x16x32_bf16 v[16:19], v[182:185], v[240:243], v[16:19]
	v_mfma_f32_16x16x32_bf16 v[0:3], v[182:185], v[244:247], v[0:3]
	s_waitcnt lgkmcnt(2)
	v_mfma_f32_16x16x32_bf16 v[126:129], v[158:161], v[186:189], v[126:129]
	ds_read_b128 v[182:185], v139 offset:3072
	v_mfma_f32_16x16x32_bf16 v[108:111], v[158:161], v[190:193], v[108:111]
	ds_read_b128 v[232:235], v112 offset:4096
	ds_read_b128 v[236:239], v112 offset:5120
	v_mfma_f32_16x16x32_bf16 v[92:95], v[158:161], v[194:197], v[92:95]
	ds_read_b128 v[240:243], v112 offset:6144
	ds_read_b128 v[244:247], v112 offset:7168
	s_mov_b32 m0, s10
	v_mfma_f32_16x16x32_bf16 v[76:79], v[158:161], v[198:201], v[76:79]
	global_load_lds_dwordx4 v[154:155], off
	v_lshl_add_u64 v[154:155], v[154:155], 0, 64
	s_waitcnt lgkmcnt(6)
	v_mfma_f32_16x16x32_bf16 v[122:125], v[162:165], v[186:189], v[122:125]
	v_mfma_f32_16x16x32_bf16 v[104:107], v[162:165], v[190:193], v[104:107]
	v_mfma_f32_16x16x32_bf16 v[88:91], v[162:165], v[194:197], v[88:91]
	s_mov_b32 m0, s18
	v_mfma_f32_16x16x32_bf16 v[72:75], v[162:165], v[198:201], v[72:75]
	global_load_lds_dwordx4 v[152:153], off
	v_lshl_add_u64 v[152:153], v[152:153], 0, 64
	s_waitcnt lgkmcnt(5)
	v_mfma_f32_16x16x32_bf16 v[118:121], v[166:169], v[186:189], v[118:121]
	v_mfma_f32_16x16x32_bf16 v[100:103], v[166:169], v[190:193], v[100:103]
	v_mfma_f32_16x16x32_bf16 v[84:87], v[166:169], v[194:197], v[84:87]
	s_mov_b32 m0, s11
	v_mfma_f32_16x16x32_bf16 v[68:71], v[166:169], v[198:201], v[68:71]
	global_load_lds_dwordx4 v[150:151], off
	v_lshl_add_u64 v[150:151], v[150:151], 0, 64
	s_waitcnt lgkmcnt(4)
	v_mfma_f32_16x16x32_bf16 v[114:117], v[182:185], v[186:189], v[114:117]
	v_mfma_f32_16x16x32_bf16 v[96:99], v[182:185], v[190:193], v[96:99]
	v_mfma_f32_16x16x32_bf16 v[80:83], v[182:185], v[194:197], v[80:83]
	s_mov_b32 m0, s9
	v_mfma_f32_16x16x32_bf16 v[64:67], v[182:185], v[198:201], v[64:67]
	global_load_lds_dwordx4 v[148:149], off
	v_lshl_add_u64 v[148:149], v[148:149], 0, 64
	s_cbranch_scc0 .Lgsk0_loop
	s_waitcnt lgkmcnt(0)
	v_mfma_f32_16x16x32_bf16 v[60:63], v[158:161], v[232:235], v[60:63]
	v_mfma_f32_16x16x32_bf16 v[44:47], v[158:161], v[236:239], v[44:47]
	v_mfma_f32_16x16x32_bf16 v[28:31], v[158:161], v[240:243], v[28:31]
	v_mfma_f32_16x16x32_bf16 v[12:15], v[158:161], v[244:247], v[12:15]
	v_mfma_f32_16x16x32_bf16 v[56:59], v[162:165], v[232:235], v[56:59]
	v_mfma_f32_16x16x32_bf16 v[40:43], v[162:165], v[236:239], v[40:43]
	v_mfma_f32_16x16x32_bf16 v[24:27], v[162:165], v[240:243], v[24:27]
	v_mfma_f32_16x16x32_bf16 v[8:11], v[162:165], v[244:247], v[8:11]
	v_mfma_f32_16x16x32_bf16 v[52:55], v[166:169], v[232:235], v[52:55]
	v_mfma_f32_16x16x32_bf16 v[36:39], v[166:169], v[236:239], v[36:39]
	v_mfma_f32_16x16x32_bf16 v[20:23], v[166:169], v[240:243], v[20:23]
	v_mfma_f32_16x16x32_bf16 v[4:7], v[166:169], v[244:247], v[4:7]
	v_mfma_f32_16x16x32_bf16 v[48:51], v[182:185], v[232:235], v[48:51]
	v_mfma_f32_16x16x32_bf16 v[32:35], v[182:185], v[236:239], v[32:35]
	v_mfma_f32_16x16x32_bf16 v[16:19], v[182:185], v[240:243], v[16:19]
	v_mfma_f32_16x16x32_bf16 v[0:3], v[182:185], v[244:247], v[0:3]
	s_waitcnt vmcnt(8)
	s_barrier
	v_add_u32_e32 v112, 0x8000, v135
	v_or_b32_e32 v139, 0x8000, v137
	ds_read_b128 v[148:151], v139
	ds_read_b128 v[152:155], v139 offset:1024
	ds_read_b128 v[158:161], v139 offset:2048
	ds_read_b128 v[162:165], v139 offset:3072
	ds_read_b128 v[166:169], v112
	ds_read_b128 v[182:185], v112 offset:1024
	ds_read_b128 v[186:189], v112 offset:2048
	ds_read_b128 v[190:193], v112 offset:3072
	v_or_b32_e32 v139, 0x10000, v137
	s_waitcnt lgkmcnt(0)
	s_lshl_b32 s7, s4, 8
	v_mfma_f32_16x16x32_bf16 v[126:129], v[148:151], v[166:169], v[126:129]
	s_and_b32 s4, s4, 0xc0
	s_and_b32 s78, s7, 0xffffc000
	s_or_b32 s8, s5, s4
	v_mfma_f32_16x16x32_bf16 v[122:125], v[152:155], v[166:169], v[122:125]
	s_mov_b64 s[4:5], -1
	s_cmpk_gt_i32 s8, 0x17f
	v_mfma_f32_16x16x32_bf16 v[118:121], v[158:161], v[166:169], v[118:121]
	v_mfma_f32_16x16x32_bf16 v[114:117], v[162:165], v[166:169], v[114:117]
	v_mfma_f32_16x16x32_bf16 v[108:111], v[148:151], v[182:185], v[108:111]
	v_mfma_f32_16x16x32_bf16 v[104:107], v[152:155], v[182:185], v[104:107]
	v_mfma_f32_16x16x32_bf16 v[100:103], v[158:161], v[182:185], v[100:103]
	v_mfma_f32_16x16x32_bf16 v[96:99], v[162:165], v[182:185], v[96:99]
	v_mfma_f32_16x16x32_bf16 v[92:95], v[148:151], v[186:189], v[92:95]
	v_mfma_f32_16x16x32_bf16 v[88:91], v[152:155], v[186:189], v[88:91]
	v_mfma_f32_16x16x32_bf16 v[84:87], v[158:161], v[186:189], v[84:87]
	v_mfma_f32_16x16x32_bf16 v[80:83], v[162:165], v[186:189], v[80:83]
	v_mfma_f32_16x16x32_bf16 v[76:79], v[148:151], v[190:193], v[76:79]
	v_mfma_f32_16x16x32_bf16 v[72:75], v[152:155], v[190:193], v[72:75]
	v_mfma_f32_16x16x32_bf16 v[68:71], v[158:161], v[190:193], v[68:71]
	v_mfma_f32_16x16x32_bf16 v[64:67], v[162:165], v[190:193], v[64:67]
	ds_read_b128 v[166:169], v112 offset:4096
	ds_read_b128 v[182:185], v112 offset:5120
	ds_read_b128 v[186:189], v112 offset:6144
	ds_read_b128 v[190:193], v112 offset:7168
	s_waitcnt lgkmcnt(0)
	s_waitcnt vmcnt(4)
	s_barrier
	v_mfma_f32_16x16x32_bf16 v[60:63], v[148:151], v[166:169], v[60:63]
	v_add_u32_e32 v112, 0x10000, v135
	v_mfma_f32_16x16x32_bf16 v[56:59], v[152:155], v[166:169], v[56:59]
	v_mfma_f32_16x16x32_bf16 v[52:55], v[158:161], v[166:169], v[52:55]
	v_mfma_f32_16x16x32_bf16 v[48:51], v[162:165], v[166:169], v[48:51]
	v_mfma_f32_16x16x32_bf16 v[44:47], v[148:151], v[182:185], v[44:47]
	v_mfma_f32_16x16x32_bf16 v[40:43], v[152:155], v[182:185], v[40:43]
	v_mfma_f32_16x16x32_bf16 v[36:39], v[158:161], v[182:185], v[36:39]
	v_mfma_f32_16x16x32_bf16 v[32:35], v[162:165], v[182:185], v[32:35]
	v_mfma_f32_16x16x32_bf16 v[28:31], v[148:151], v[186:189], v[28:31]
	v_mfma_f32_16x16x32_bf16 v[24:27], v[152:155], v[186:189], v[24:27]
	v_mfma_f32_16x16x32_bf16 v[20:23], v[158:161], v[186:189], v[20:23]
	v_mfma_f32_16x16x32_bf16 v[16:19], v[162:165], v[186:189], v[16:19]
	v_mfma_f32_16x16x32_bf16 v[12:15], v[148:151], v[190:193], v[12:15]
	v_mfma_f32_16x16x32_bf16 v[8:11], v[152:155], v[190:193], v[8:11]
	v_mfma_f32_16x16x32_bf16 v[4:7], v[158:161], v[190:193], v[4:7]
	v_mfma_f32_16x16x32_bf16 v[0:3], v[162:165], v[190:193], v[0:3]
	ds_read_b128 v[148:151], v139
	ds_read_b128 v[152:155], v139 offset:1024
	ds_read_b128 v[158:161], v139 offset:2048
	ds_read_b128 v[162:165], v139 offset:3072
	ds_read_b128 v[166:169], v112
	ds_read_b128 v[182:185], v112 offset:1024
	ds_read_b128 v[186:189], v112 offset:2048
	ds_read_b128 v[190:193], v112 offset:3072
	s_nop 0
	s_waitcnt lgkmcnt(0)
	s_nop 0
	v_mfma_f32_16x16x32_bf16 v[126:129], v[148:151], v[166:169], v[126:129]
	v_mfma_f32_16x16x32_bf16 v[122:125], v[152:155], v[166:169], v[122:125]
	v_mfma_f32_16x16x32_bf16 v[118:121], v[158:161], v[166:169], v[118:121]
	v_mfma_f32_16x16x32_bf16 v[114:117], v[162:165], v[166:169], v[114:117]
	v_mfma_f32_16x16x32_bf16 v[108:111], v[148:151], v[182:185], v[108:111]
	v_mfma_f32_16x16x32_bf16 v[104:107], v[152:155], v[182:185], v[104:107]
	v_mfma_f32_16x16x32_bf16 v[100:103], v[158:161], v[182:185], v[100:103]
	v_mfma_f32_16x16x32_bf16 v[96:99], v[162:165], v[182:185], v[96:99]
	v_mfma_f32_16x16x32_bf16 v[92:95], v[148:151], v[186:189], v[92:95]
	v_mfma_f32_16x16x32_bf16 v[88:91], v[152:155], v[186:189], v[88:91]
	v_mfma_f32_16x16x32_bf16 v[84:87], v[158:161], v[186:189], v[84:87]
	v_mfma_f32_16x16x32_bf16 v[80:83], v[162:165], v[186:189], v[80:83]
	v_mfma_f32_16x16x32_bf16 v[76:79], v[148:151], v[190:193], v[76:79]
	v_mfma_f32_16x16x32_bf16 v[72:75], v[152:155], v[190:193], v[72:75]
	v_mfma_f32_16x16x32_bf16 v[68:71], v[158:161], v[190:193], v[68:71]
	v_mfma_f32_16x16x32_bf16 v[64:67], v[162:165], v[190:193], v[64:67]
	ds_read_b128 v[166:169], v112 offset:4096
	ds_read_b128 v[182:185], v112 offset:5120
	ds_read_b128 v[186:189], v112 offset:6144
	ds_read_b128 v[190:193], v112 offset:7168
	s_waitcnt lgkmcnt(0)
	s_waitcnt vmcnt(0)
	s_barrier
	v_mfma_f32_16x16x32_bf16 v[60:63], v[148:151], v[166:169], v[60:63]
	v_add_u32_e32 v112, 0x18000, v135
	v_or_b32_e32 v135, 0x18000, v137
	v_mfma_f32_16x16x32_bf16 v[56:59], v[152:155], v[166:169], v[56:59]
	v_bfe_u32 v137, v131, 4, 2
	v_mfma_f32_16x16x32_bf16 v[52:55], v[158:161], v[166:169], v[52:55]
	v_mfma_f32_16x16x32_bf16 v[48:51], v[162:165], v[166:169], v[48:51]
	v_mfma_f32_16x16x32_bf16 v[44:47], v[148:151], v[182:185], v[44:47]
	v_mfma_f32_16x16x32_bf16 v[40:43], v[152:155], v[182:185], v[40:43]
	v_mfma_f32_16x16x32_bf16 v[36:39], v[158:161], v[182:185], v[36:39]
	v_mfma_f32_16x16x32_bf16 v[32:35], v[162:165], v[182:185], v[32:35]
	v_mfma_f32_16x16x32_bf16 v[28:31], v[148:151], v[186:189], v[28:31]
	v_mfma_f32_16x16x32_bf16 v[24:27], v[152:155], v[186:189], v[24:27]
	v_mfma_f32_16x16x32_bf16 v[20:23], v[158:161], v[186:189], v[20:23]
	v_mfma_f32_16x16x32_bf16 v[16:19], v[162:165], v[186:189], v[16:19]
	v_mfma_f32_16x16x32_bf16 v[12:15], v[148:151], v[190:193], v[12:15]
	v_mfma_f32_16x16x32_bf16 v[8:11], v[152:155], v[190:193], v[8:11]
	v_mfma_f32_16x16x32_bf16 v[4:7], v[158:161], v[190:193], v[4:7]
	v_mfma_f32_16x16x32_bf16 v[0:3], v[162:165], v[190:193], v[0:3]
	ds_read_b128 v[164:167], v135
	ds_read_b128 v[168:171], v135 offset:1024
	ds_read_b128 v[182:185], v135 offset:2048
	ds_read_b128 v[186:189], v135 offset:3072
	ds_read_b128 v[148:151], v112
	ds_read_b128 v[152:155], v112 offset:1024
	ds_read_b128 v[158:161], v112 offset:2048
	ds_read_b128 v[190:193], v112 offset:3072
	v_or_b32_e32 v162, 16, v144
	s_waitcnt lgkmcnt(0)
	v_ashrrev_i32_e32 v163, 31, v162
	v_mfma_f32_16x16x32_bf16 v[126:129], v[164:167], v[148:151], v[126:129]
	v_and_b32_e32 v135, 63, v131
	v_mfma_f32_16x16x32_bf16 v[122:125], v[168:171], v[148:151], v[122:125]
	v_mfma_f32_16x16x32_bf16 v[118:121], v[182:185], v[148:151], v[118:121]
	v_mfma_f32_16x16x32_bf16 v[114:117], v[186:189], v[148:151], v[114:117]
	v_mfma_f32_16x16x32_bf16 v[108:111], v[164:167], v[152:155], v[108:111]
	v_mfma_f32_16x16x32_bf16 v[104:107], v[168:171], v[152:155], v[104:107]
	v_mfma_f32_16x16x32_bf16 v[100:103], v[182:185], v[152:155], v[100:103]
	v_mfma_f32_16x16x32_bf16 v[96:99], v[186:189], v[152:155], v[96:99]
	v_mfma_f32_16x16x32_bf16 v[92:95], v[164:167], v[158:161], v[92:95]
	v_mfma_f32_16x16x32_bf16 v[88:91], v[168:171], v[158:161], v[88:91]
	v_mfma_f32_16x16x32_bf16 v[84:87], v[182:185], v[158:161], v[84:87]
	v_mfma_f32_16x16x32_bf16 v[80:83], v[186:189], v[158:161], v[80:83]
	v_or_b32_e32 v160, 32, v144
	v_or_b32_e32 v158, 48, v144
	v_ashrrev_i32_e32 v161, 31, v160
	v_mfma_f32_16x16x32_bf16 v[76:79], v[164:167], v[190:193], v[76:79]
	v_ashrrev_i32_e32 v159, 31, v158
	v_mfma_f32_16x16x32_bf16 v[72:75], v[168:171], v[190:193], v[72:75]
	v_mfma_f32_16x16x32_bf16 v[68:71], v[182:185], v[190:193], v[68:71]
	v_mfma_f32_16x16x32_bf16 v[64:67], v[186:189], v[190:193], v[64:67]
	ds_read_b128 v[148:151], v112 offset:4096
	ds_read_b128 v[152:155], v112 offset:5120
	ds_read_b128 v[190:193], v112 offset:6144
	ds_read_b128 v[194:197], v112 offset:7168
	s_waitcnt lgkmcnt(0)
	s_barrier
	v_mfma_f32_16x16x32_bf16 v[60:63], v[164:167], v[148:151], v[60:63]
	v_mfma_f32_16x16x32_bf16 v[56:59], v[168:171], v[148:151], v[56:59]
	v_mfma_f32_16x16x32_bf16 v[52:55], v[182:185], v[148:151], v[52:55]
	v_mfma_f32_16x16x32_bf16 v[48:51], v[186:189], v[148:151], v[48:51]
	v_or_b32_e32 v150, 0x60, v144
	v_or_b32_e32 v148, 0x70, v144
	v_ashrrev_i32_e32 v151, 31, v150
	v_mfma_f32_16x16x32_bf16 v[44:47], v[164:167], v[152:155], v[44:47]
	v_ashrrev_i32_e32 v149, 31, v148
	v_mfma_f32_16x16x32_bf16 v[40:43], v[168:171], v[152:155], v[40:43]
	v_mfma_f32_16x16x32_bf16 v[36:39], v[182:185], v[152:155], v[36:39]
	v_mfma_f32_16x16x32_bf16 v[32:35], v[186:189], v[152:155], v[32:35]
	v_or_b32_e32 v154, 64, v144
	v_or_b32_e32 v152, 0x50, v144
	v_ashrrev_i32_e32 v155, 31, v154
	v_mfma_f32_16x16x32_bf16 v[28:31], v[164:167], v[190:193], v[28:31]
	v_ashrrev_i32_e32 v153, 31, v152
	v_mfma_f32_16x16x32_bf16 v[24:27], v[168:171], v[190:193], v[24:27]
	v_mfma_f32_16x16x32_bf16 v[20:23], v[182:185], v[190:193], v[20:23]
	v_mfma_f32_16x16x32_bf16 v[16:19], v[186:189], v[190:193], v[16:19]
	v_mfma_f32_16x16x32_bf16 v[12:15], v[164:167], v[194:197], v[12:15]
	v_mfma_f32_16x16x32_bf16 v[8:11], v[168:171], v[194:197], v[8:11]
	v_mfma_f32_16x16x32_bf16 v[4:7], v[182:185], v[194:197], v[4:7]
	v_mfma_f32_16x16x32_bf16 v[0:3], v[186:189], v[194:197], v[0:3]
	s_cbranch_scc0 .LBB0_213
	s_cmpk_gt_u32 s8, 0x57f
	s_cbranch_scc0 .LBB0_210
	s_cmpk_lg_i32 s8, 0x580
	s_cbranch_scc1 .LBB0_209
	v_lshlrev_b32_e32 v112, 7, v144
	v_and_b32_e32 v112, 0x7c780, v112
	v_lshl_add_u64 v[164:165], s[46:47], 0, v[112:113]
	v_lshlrev_b32_e32 v112, 5, v137
	v_lshl_add_u64 v[168:169], v[164:165], 0, v[112:113]
	global_load_dwordx4 v[164:167], v[168:169], off offset:16
	s_nop 0
	global_load_dwordx4 v[168:171], v[168:169], off
	v_pk_mul_f32 v[184:185], v[146:147], v[122:123] op_sel_hi:[0,1]
	v_pk_mul_f32 v[176:177], v[146:147], v[126:127] op_sel_hi:[0,1]
	v_pk_mul_f32 v[182:183], v[146:147], v[124:125] op_sel_hi:[0,1]
	v_pk_mul_f32 v[174:175], v[146:147], v[128:129] op_sel_hi:[0,1]
	v_lshlrev_b32_e32 v139, 7, v162
	s_waitcnt vmcnt(0)
	v_mov_b32_e32 v186, v168
	v_mov_b32_e32 v187, v170
	v_mov_b32_e32 v170, v169
	v_pk_mul_f32 v[168:169], v[184:185], v[170:171]
	v_pk_mul_f32 v[184:185], v[184:185], v[186:187]
	v_pk_fma_f32 v[168:169], v[176:177], v[186:187], v[168:169] neg_lo:[0,0,1] neg_hi:[0,0,1]
	v_pk_fma_f32 v[170:171], v[176:177], v[170:171], v[184:185]
	v_mov_b32_e32 v177, v166
	v_mov_b32_e32 v166, v165
	v_mov_b32_e32 v176, v164
	v_pk_mul_f32 v[164:165], v[182:183], v[166:167]
	v_cvt_pk_bf16_f32 v168, v168, v169
	v_pk_fma_f32 v[164:165], v[174:175], v[176:177], v[164:165] neg_lo:[0,0,1] neg_hi:[0,0,1]
	v_pk_mul_f32 v[176:177], v[182:183], v[176:177]
	v_cvt_pk_bf16_f32 v169, v164, v165
	v_lshlrev_b64 v[164:165], 6, v[144:145]
	v_pk_fma_f32 v[166:167], v[174:175], v[166:167], v[176:177]
	v_lshl_add_u64 v[174:175], s[36:37], 0, v[164:165]
	v_lshlrev_b32_e32 v164, 3, v137
	v_mov_b32_e32 v165, v113
	v_lshl_add_u64 v[174:175], v[174:175], 0, v[164:165]
	global_store_dwordx2 v[174:175], v[168:169], off
	v_cvt_pk_bf16_f32 v169, v166, v167
	v_and_b32_e32 v166, 0x7cf80, v139
	v_mov_b32_e32 v167, v113
	v_cvt_pk_bf16_f32 v168, v170, v171
	v_lshl_add_u64 v[166:167], s[46:47], 0, v[166:167]
	global_store_dwordx2 v[174:175], v[168:169], off offset:32
	v_lshl_add_u64 v[182:183], v[166:167], 0, v[112:113]
	global_load_dwordx4 v[166:169], v[182:183], off offset:16
	s_nop 0
	global_load_dwordx4 v[182:185], v[182:183], off
	v_pk_mul_f32 v[186:187], v[142:143], v[104:105] op_sel_hi:[0,1]
	v_pk_mul_f32 v[174:175], v[142:143], v[108:109] op_sel_hi:[0,1]
	v_pk_mul_f32 v[176:177], v[142:143], v[106:107] op_sel_hi:[0,1]
	v_pk_mul_f32 v[170:171], v[142:143], v[110:111] op_sel_hi:[0,1]
	v_lshlrev_b32_e32 v139, 7, v160
	s_waitcnt vmcnt(0)
	v_mov_b32_e32 v188, v182
	v_mov_b32_e32 v189, v184
	v_mov_b32_e32 v184, v183
	v_pk_mul_f32 v[182:183], v[186:187], v[184:185]
	v_pk_mul_f32 v[186:187], v[186:187], v[188:189]
	v_pk_fma_f32 v[182:183], v[174:175], v[188:189], v[182:183] neg_lo:[0,0,1] neg_hi:[0,0,1]
	v_pk_fma_f32 v[174:175], v[174:175], v[184:185], v[186:187]
	v_mov_b32_e32 v185, v168
	v_mov_b32_e32 v168, v167
	v_mov_b32_e32 v184, v166
	v_pk_mul_f32 v[166:167], v[176:177], v[168:169]
	v_pk_mul_f32 v[176:177], v[176:177], v[184:185]
	v_pk_fma_f32 v[166:167], v[170:171], v[184:185], v[166:167] neg_lo:[0,0,1] neg_hi:[0,0,1]
	v_pk_fma_f32 v[168:169], v[170:171], v[168:169], v[176:177]
	v_cvt_pk_bf16_f32 v171, v166, v167
	v_lshlrev_b64 v[166:167], 6, v[162:163]
	v_lshl_add_u64 v[166:167], s[36:37], 0, v[166:167]
	v_cvt_pk_bf16_f32 v170, v182, v183
	v_lshl_add_u64 v[166:167], v[166:167], 0, v[164:165]
	global_store_dwordx2 v[166:167], v[170:171], off
	v_cvt_pk_bf16_f32 v170, v174, v175
	v_cvt_pk_bf16_f32 v171, v168, v169
	global_store_dwordx2 v[166:167], v[170:171], off offset:32
	v_and_b32_e32 v166, 0x7d780, v139
	v_mov_b32_e32 v167, v113
	v_lshl_add_u64 v[166:167], s[46:47], 0, v[166:167]
	v_lshl_add_u64 v[182:183], v[166:167], 0, v[112:113]
	global_load_dwordx4 v[166:169], v[182:183], off offset:16
	s_nop 0
	global_load_dwordx4 v[182:185], v[182:183], off
	v_pk_mul_f32 v[186:187], v[140:141], v[88:89] op_sel_hi:[0,1]
	v_pk_mul_f32 v[174:175], v[140:141], v[92:93] op_sel_hi:[0,1]
	v_pk_mul_f32 v[176:177], v[140:141], v[90:91] op_sel_hi:[0,1]
	v_pk_mul_f32 v[170:171], v[140:141], v[94:95] op_sel_hi:[0,1]
	s_waitcnt vmcnt(0)
	v_mov_b32_e32 v188, v182
	v_mov_b32_e32 v189, v184
	v_mov_b32_e32 v184, v183
	v_pk_mul_f32 v[182:183], v[186:187], v[184:185]
	v_pk_mul_f32 v[186:187], v[186:187], v[188:189]
	v_pk_fma_f32 v[182:183], v[174:175], v[188:189], v[182:183] neg_lo:[0,0,1] neg_hi:[0,0,1]
	v_pk_fma_f32 v[174:175], v[174:175], v[184:185], v[186:187]
	v_mov_b32_e32 v185, v168
	v_mov_b32_e32 v168, v167
	v_mov_b32_e32 v184, v166
	v_pk_mul_f32 v[166:167], v[176:177], v[168:169]
	v_pk_mul_f32 v[176:177], v[176:177], v[184:185]
	v_pk_fma_f32 v[166:167], v[170:171], v[184:185], v[166:167] neg_lo:[0,0,1] neg_hi:[0,0,1]
	v_pk_fma_f32 v[168:169], v[170:171], v[168:169], v[176:177]
	v_cvt_pk_bf16_f32 v171, v166, v167
	v_lshlrev_b64 v[166:167], 6, v[160:161]
	v_lshl_add_u64 v[166:167], s[36:37], 0, v[166:167]
	v_cvt_pk_bf16_f32 v170, v182, v183
	v_lshl_add_u64 v[166:167], v[166:167], 0, v[164:165]
	global_store_dwordx2 v[166:167], v[170:171], off
	v_cvt_pk_bf16_f32 v170, v174, v175
	v_cvt_pk_bf16_f32 v171, v168, v169
	global_store_dwordx2 v[166:167], v[170:171], off offset:32
	v_pk_mul_f32 v[170:171], v[138:139], v[78:79] op_sel_hi:[0,1]
	v_pk_mul_f32 v[174:175], v[138:139], v[76:77] op_sel_hi:[0,1]
	v_pk_mul_f32 v[176:177], v[138:139], v[74:75] op_sel_hi:[0,1]
	v_pk_mul_f32 v[186:187], v[138:139], v[72:73] op_sel_hi:[0,1]
	v_lshlrev_b32_e32 v139, 7, v158
	v_and_b32_e32 v166, 0x7df80, v139
	v_mov_b32_e32 v167, v113
	v_lshl_add_u64 v[166:167], s[46:47], 0, v[166:167]
	v_lshl_add_u64 v[182:183], v[166:167], 0, v[112:113]
	global_load_dwordx4 v[166:169], v[182:183], off offset:16
	s_nop 0
	global_load_dwordx4 v[182:185], v[182:183], off
	v_lshlrev_b32_e32 v139, 7, v154
	s_waitcnt vmcnt(0)
	v_mov_b32_e32 v188, v182
	v_mov_b32_e32 v189, v184
	v_mov_b32_e32 v184, v183
	v_pk_mul_f32 v[182:183], v[186:187], v[184:185]
	v_pk_mul_f32 v[186:187], v[186:187], v[188:189]
	v_pk_fma_f32 v[182:183], v[174:175], v[188:189], v[182:183] neg_lo:[0,0,1] neg_hi:[0,0,1]
	v_pk_fma_f32 v[174:175], v[174:175], v[184:185], v[186:187]
	v_mov_b32_e32 v185, v168
	v_mov_b32_e32 v168, v167
	v_mov_b32_e32 v184, v166
	v_pk_mul_f32 v[166:167], v[176:177], v[168:169]
	v_pk_mul_f32 v[176:177], v[176:177], v[184:185]
	v_pk_fma_f32 v[166:167], v[170:171], v[184:185], v[166:167] neg_lo:[0,0,1] neg_hi:[0,0,1]
	v_pk_fma_f32 v[168:169], v[170:171], v[168:169], v[176:177]
	v_cvt_pk_bf16_f32 v171, v166, v167
	v_lshlrev_b64 v[166:167], 6, v[158:159]
	v_lshl_add_u64 v[166:167], s[36:37], 0, v[166:167]
	v_cvt_pk_bf16_f32 v170, v182, v183
	v_lshl_add_u64 v[166:167], v[166:167], 0, v[164:165]
	global_store_dwordx2 v[166:167], v[170:171], off
	v_cvt_pk_bf16_f32 v170, v174, v175
	v_cvt_pk_bf16_f32 v171, v168, v169
	global_store_dwordx2 v[166:167], v[170:171], off offset:32
	v_and_b32_e32 v166, 0x7e780, v139
	v_mov_b32_e32 v167, v113
	v_lshl_add_u64 v[166:167], s[46:47], 0, v[166:167]
	v_lshl_add_u64 v[182:183], v[166:167], 0, v[112:113]
	global_load_dwordx4 v[166:169], v[182:183], off offset:16
	s_nop 0
	global_load_dwordx4 v[182:185], v[182:183], off
	v_pk_mul_f32 v[186:187], v[136:137], v[56:57] op_sel_hi:[0,1]
	v_pk_mul_f32 v[174:175], v[136:137], v[60:61] op_sel_hi:[0,1]
	v_pk_mul_f32 v[176:177], v[136:137], v[58:59] op_sel_hi:[0,1]
	v_pk_mul_f32 v[170:171], v[136:137], v[62:63] op_sel_hi:[0,1]
	v_lshlrev_b32_e32 v139, 7, v152
	s_waitcnt vmcnt(0)
	v_mov_b32_e32 v188, v182
	v_mov_b32_e32 v189, v184
	v_mov_b32_e32 v184, v183
	v_pk_mul_f32 v[182:183], v[186:187], v[184:185]
	v_pk_mul_f32 v[186:187], v[186:187], v[188:189]
	v_pk_fma_f32 v[182:183], v[174:175], v[188:189], v[182:183] neg_lo:[0,0,1] neg_hi:[0,0,1]
	v_pk_fma_f32 v[174:175], v[174:175], v[184:185], v[186:187]
	v_mov_b32_e32 v185, v168
	v_mov_b32_e32 v168, v167
	v_mov_b32_e32 v184, v166
	v_pk_mul_f32 v[166:167], v[176:177], v[168:169]
	v_pk_mul_f32 v[176:177], v[176:177], v[184:185]
	v_pk_fma_f32 v[166:167], v[170:171], v[184:185], v[166:167] neg_lo:[0,0,1] neg_hi:[0,0,1]
	v_pk_fma_f32 v[168:169], v[170:171], v[168:169], v[176:177]
	v_cvt_pk_bf16_f32 v171, v166, v167
	v_lshlrev_b64 v[166:167], 6, v[154:155]
	v_lshl_add_u64 v[166:167], s[36:37], 0, v[166:167]
	v_cvt_pk_bf16_f32 v170, v182, v183
	v_lshl_add_u64 v[166:167], v[166:167], 0, v[164:165]
	global_store_dwordx2 v[166:167], v[170:171], off
	v_cvt_pk_bf16_f32 v170, v174, v175
	v_cvt_pk_bf16_f32 v171, v168, v169
	global_store_dwordx2 v[166:167], v[170:171], off offset:32
	v_and_b32_e32 v166, 0x7ef80, v139
	v_mov_b32_e32 v167, v113
	v_lshl_add_u64 v[166:167], s[46:47], 0, v[166:167]
	v_lshl_add_u64 v[182:183], v[166:167], 0, v[112:113]
	global_load_dwordx4 v[166:169], v[182:183], off offset:16
	s_nop 0
	global_load_dwordx4 v[182:185], v[182:183], off
	v_pk_mul_f32 v[186:187], v[134:135], v[40:41] op_sel_hi:[0,1]
	v_pk_mul_f32 v[174:175], v[134:135], v[44:45] op_sel_hi:[0,1]
	v_pk_mul_f32 v[176:177], v[134:135], v[42:43] op_sel_hi:[0,1]
	v_pk_mul_f32 v[170:171], v[134:135], v[46:47] op_sel_hi:[0,1]
	v_lshlrev_b32_e32 v139, 7, v150
	s_waitcnt vmcnt(0)
	v_mov_b32_e32 v188, v182
	v_mov_b32_e32 v189, v184
	v_mov_b32_e32 v184, v183
	v_pk_mul_f32 v[182:183], v[186:187], v[184:185]
	v_pk_mul_f32 v[186:187], v[186:187], v[188:189]
	v_pk_fma_f32 v[182:183], v[174:175], v[188:189], v[182:183] neg_lo:[0,0,1] neg_hi:[0,0,1]
	v_pk_fma_f32 v[174:175], v[174:175], v[184:185], v[186:187]
	v_mov_b32_e32 v185, v168
	v_mov_b32_e32 v168, v167
	v_mov_b32_e32 v184, v166
	v_pk_mul_f32 v[166:167], v[176:177], v[168:169]
	v_pk_mul_f32 v[176:177], v[176:177], v[184:185]
	v_pk_fma_f32 v[166:167], v[170:171], v[184:185], v[166:167] neg_lo:[0,0,1] neg_hi:[0,0,1]
	v_pk_fma_f32 v[168:169], v[170:171], v[168:169], v[176:177]
	v_cvt_pk_bf16_f32 v171, v166, v167
	v_lshlrev_b64 v[166:167], 6, v[152:153]
	v_lshl_add_u64 v[166:167], s[36:37], 0, v[166:167]
	v_cvt_pk_bf16_f32 v170, v182, v183
	v_lshl_add_u64 v[166:167], v[166:167], 0, v[164:165]
	global_store_dwordx2 v[166:167], v[170:171], off
	v_cvt_pk_bf16_f32 v170, v174, v175
	v_cvt_pk_bf16_f32 v171, v168, v169
	global_store_dwordx2 v[166:167], v[170:171], off offset:32
	v_and_b32_e32 v166, 0x7f780, v139
	v_mov_b32_e32 v167, v113
	v_lshl_add_u64 v[166:167], s[46:47], 0, v[166:167]
	v_lshl_add_u64 v[182:183], v[166:167], 0, v[112:113]
	global_load_dwordx4 v[166:169], v[182:183], off offset:16
	s_nop 0
	global_load_dwordx4 v[182:185], v[182:183], off
	v_pk_mul_f32 v[186:187], v[132:133], v[24:25] op_sel_hi:[0,1]
	v_pk_mul_f32 v[174:175], v[132:133], v[28:29] op_sel_hi:[0,1]
	v_pk_mul_f32 v[176:177], v[132:133], v[26:27] op_sel_hi:[0,1]
	v_pk_mul_f32 v[170:171], v[132:133], v[30:31] op_sel_hi:[0,1]
	v_lshlrev_b32_e32 v139, 7, v148
	s_waitcnt vmcnt(0)
	v_mov_b32_e32 v188, v182
	v_mov_b32_e32 v189, v184
	v_mov_b32_e32 v184, v183
	v_pk_mul_f32 v[182:183], v[186:187], v[184:185]
	v_pk_mul_f32 v[186:187], v[186:187], v[188:189]
	v_pk_fma_f32 v[182:183], v[174:175], v[188:189], v[182:183] neg_lo:[0,0,1] neg_hi:[0,0,1]
	v_pk_fma_f32 v[174:175], v[174:175], v[184:185], v[186:187]
	v_mov_b32_e32 v185, v168
	v_mov_b32_e32 v168, v167
	v_mov_b32_e32 v184, v166
	v_pk_mul_f32 v[166:167], v[176:177], v[168:169]
	v_pk_mul_f32 v[176:177], v[176:177], v[184:185]
	v_pk_fma_f32 v[166:167], v[170:171], v[184:185], v[166:167] neg_lo:[0,0,1] neg_hi:[0,0,1]
	v_pk_fma_f32 v[168:169], v[170:171], v[168:169], v[176:177]
	v_cvt_pk_bf16_f32 v171, v166, v167
	v_lshlrev_b64 v[166:167], 6, v[150:151]
	v_lshl_add_u64 v[166:167], s[36:37], 0, v[166:167]
	v_cvt_pk_bf16_f32 v170, v182, v183
	v_lshl_add_u64 v[166:167], v[166:167], 0, v[164:165]
	global_store_dwordx2 v[166:167], v[170:171], off
	v_cvt_pk_bf16_f32 v170, v174, v175
	v_cvt_pk_bf16_f32 v171, v168, v169
	global_store_dwordx2 v[166:167], v[170:171], off offset:32
	v_and_b32_e32 v166, 0x7ff80, v139
	v_mov_b32_e32 v167, v113
	v_lshl_add_u64 v[166:167], s[46:47], 0, v[166:167]
	v_lshl_add_u64 v[182:183], v[166:167], 0, v[112:113]
	global_load_dwordx4 v[166:169], v[182:183], off offset:16
	s_nop 0
	global_load_dwordx4 v[182:185], v[182:183], off
	v_pk_mul_f32 v[186:187], v[130:131], v[8:9] op_sel_hi:[0,1]
	v_pk_mul_f32 v[174:175], v[130:131], v[12:13] op_sel_hi:[0,1]
	v_pk_mul_f32 v[176:177], v[130:131], v[10:11] op_sel_hi:[0,1]
	v_pk_mul_f32 v[170:171], v[130:131], v[14:15] op_sel_hi:[0,1]
	s_waitcnt vmcnt(0)
	v_mov_b32_e32 v188, v182
	v_mov_b32_e32 v189, v184
	v_mov_b32_e32 v184, v183
	v_pk_mul_f32 v[182:183], v[186:187], v[184:185]
	v_pk_mul_f32 v[186:187], v[186:187], v[188:189]
	v_pk_fma_f32 v[182:183], v[174:175], v[188:189], v[182:183] neg_lo:[0,0,1] neg_hi:[0,0,1]
	v_pk_fma_f32 v[174:175], v[174:175], v[184:185], v[186:187]
	v_mov_b32_e32 v185, v168
	v_mov_b32_e32 v168, v167
	v_mov_b32_e32 v184, v166
	v_pk_mul_f32 v[166:167], v[176:177], v[168:169]
	v_pk_mul_f32 v[176:177], v[176:177], v[184:185]
	v_pk_fma_f32 v[166:167], v[170:171], v[184:185], v[166:167] neg_lo:[0,0,1] neg_hi:[0,0,1]
	v_pk_fma_f32 v[168:169], v[170:171], v[168:169], v[176:177]
	v_cvt_pk_bf16_f32 v171, v166, v167
	v_lshlrev_b64 v[166:167], 6, v[148:149]
	v_lshl_add_u64 v[166:167], s[36:37], 0, v[166:167]
	v_cvt_pk_bf16_f32 v170, v182, v183
	v_lshl_add_u64 v[164:165], v[166:167], 0, v[164:165]
	v_cvt_pk_bf16_f32 v166, v174, v175
	v_cvt_pk_bf16_f32 v167, v168, v169
	global_store_dwordx2 v[164:165], v[170:171], off
	global_store_dwordx2 v[164:165], v[166:167], off offset:32

.Lgsk1_loop:
	s_add_i32 s9, s8, 0xfffe8000
	s_and_b32 s10, s8, 0x18000
	s_waitcnt vmcnt(8) lgkmcnt(0)
	s_barrier
	s_and_b32 s9, s9, 0x18000
	s_add_i32 s10, s7, s10
	v_add_u32_e32 v112, s9, v139
	v_or_b32_e32 v141, s9, v140
	s_add_i32 s18, s10, 0x400
	s_add_i32 s11, s10, 0x800
	s_add_i32 s9, s10, 0xc00
	s_add_i32 s8, s8, 0x8000
	s_cmp_eq_u32 s8, 0x100000
	ds_read_b128 v[162:165], v112
	ds_read_b128 v[166:169], v112 offset:1024
	ds_read_b128 v[174:177], v112 offset:2048
	ds_read_b128 v[182:185], v112 offset:3072
	v_mfma_f32_16x16x32_bf16 v[60:63], v[142:145], v[232:235], v[60:63]
	v_mfma_f32_16x16x32_bf16 v[44:47], v[142:145], v[236:239], v[44:47]
	v_mfma_f32_16x16x32_bf16 v[28:31], v[142:145], v[240:243], v[28:31]
	v_mfma_f32_16x16x32_bf16 v[12:15], v[142:145], v[244:247], v[12:15]
	v_mfma_f32_16x16x32_bf16 v[56:59], v[146:149], v[232:235], v[56:59]
	ds_read_b128 v[142:145], v141
	v_mfma_f32_16x16x32_bf16 v[40:43], v[146:149], v[236:239], v[40:43]
	v_mfma_f32_16x16x32_bf16 v[24:27], v[146:149], v[240:243], v[24:27]
	v_mfma_f32_16x16x32_bf16 v[8:11], v[146:149], v[244:247], v[8:11]
	v_mfma_f32_16x16x32_bf16 v[52:55], v[150:153], v[232:235], v[52:55]
	ds_read_b128 v[146:149], v141 offset:1024
	v_mfma_f32_16x16x32_bf16 v[36:39], v[150:153], v[236:239], v[36:39]
	v_mfma_f32_16x16x32_bf16 v[20:23], v[150:153], v[240:243], v[20:23]
	v_mfma_f32_16x16x32_bf16 v[4:7], v[150:153], v[244:247], v[4:7]
	v_mfma_f32_16x16x32_bf16 v[48:51], v[158:161], v[232:235], v[48:51]
	ds_read_b128 v[150:153], v141 offset:2048
	v_mfma_f32_16x16x32_bf16 v[32:35], v[158:161], v[236:239], v[32:35]
	v_mfma_f32_16x16x32_bf16 v[16:19], v[158:161], v[240:243], v[16:19]
	v_mfma_f32_16x16x32_bf16 v[0:3], v[158:161], v[244:247], v[0:3]
	s_waitcnt lgkmcnt(2)
	v_mfma_f32_16x16x32_bf16 v[126:129], v[142:145], v[162:165], v[126:129]
	ds_read_b128 v[158:161], v141 offset:3072
	v_mfma_f32_16x16x32_bf16 v[108:111], v[142:145], v[166:169], v[108:111]
	ds_read_b128 v[232:235], v112 offset:4096
	ds_read_b128 v[236:239], v112 offset:5120
	v_mfma_f32_16x16x32_bf16 v[92:95], v[142:145], v[174:177], v[92:95]
	ds_read_b128 v[240:243], v112 offset:6144
	ds_read_b128 v[244:247], v112 offset:7168
	s_mov_b32 m0, s10
	v_mfma_f32_16x16x32_bf16 v[76:79], v[142:145], v[182:185], v[76:79]
	global_load_lds_dwordx4 v[136:137], off
	v_lshl_add_u64 v[136:137], v[136:137], 0, 64
	s_waitcnt lgkmcnt(6)
	v_mfma_f32_16x16x32_bf16 v[122:125], v[146:149], v[162:165], v[122:125]
	v_mfma_f32_16x16x32_bf16 v[104:107], v[146:149], v[166:169], v[104:107]
	v_mfma_f32_16x16x32_bf16 v[88:91], v[146:149], v[174:177], v[88:91]
	s_mov_b32 m0, s18
	v_mfma_f32_16x16x32_bf16 v[72:75], v[146:149], v[182:185], v[72:75]
	global_load_lds_dwordx4 v[134:135], off
	v_lshl_add_u64 v[134:135], v[134:135], 0, 64
	s_waitcnt lgkmcnt(5)
	v_mfma_f32_16x16x32_bf16 v[118:121], v[150:153], v[162:165], v[118:121]
	v_mfma_f32_16x16x32_bf16 v[100:103], v[150:153], v[166:169], v[100:103]
	v_mfma_f32_16x16x32_bf16 v[84:87], v[150:153], v[174:177], v[84:87]
	s_mov_b32 m0, s11
	v_mfma_f32_16x16x32_bf16 v[68:71], v[150:153], v[182:185], v[68:71]
	global_load_lds_dwordx4 v[132:133], off
	v_lshl_add_u64 v[132:133], v[132:133], 0, 64
	s_waitcnt lgkmcnt(4)
	v_mfma_f32_16x16x32_bf16 v[114:117], v[158:161], v[162:165], v[114:117]
	v_mfma_f32_16x16x32_bf16 v[96:99], v[158:161], v[166:169], v[96:99]
	v_mfma_f32_16x16x32_bf16 v[80:83], v[158:161], v[174:177], v[80:83]
	s_mov_b32 m0, s9
	v_mfma_f32_16x16x32_bf16 v[64:67], v[158:161], v[182:185], v[64:67]
	global_load_lds_dwordx4 v[130:131], off
	v_lshl_add_u64 v[130:131], v[130:131], 0, 64
	s_cbranch_scc0 .Lgsk1_loop
	s_waitcnt lgkmcnt(0)
	v_mfma_f32_16x16x32_bf16 v[60:63], v[142:145], v[232:235], v[60:63]
	v_mfma_f32_16x16x32_bf16 v[44:47], v[142:145], v[236:239], v[44:47]
	v_mfma_f32_16x16x32_bf16 v[28:31], v[142:145], v[240:243], v[28:31]
	v_mfma_f32_16x16x32_bf16 v[12:15], v[142:145], v[244:247], v[12:15]
	v_mfma_f32_16x16x32_bf16 v[56:59], v[146:149], v[232:235], v[56:59]
	v_mfma_f32_16x16x32_bf16 v[40:43], v[146:149], v[236:239], v[40:43]
	v_mfma_f32_16x16x32_bf16 v[24:27], v[146:149], v[240:243], v[24:27]
	v_mfma_f32_16x16x32_bf16 v[8:11], v[146:149], v[244:247], v[8:11]
	v_mfma_f32_16x16x32_bf16 v[52:55], v[150:153], v[232:235], v[52:55]
	v_mfma_f32_16x16x32_bf16 v[36:39], v[150:153], v[236:239], v[36:39]
	v_mfma_f32_16x16x32_bf16 v[20:23], v[150:153], v[240:243], v[20:23]
	v_mfma_f32_16x16x32_bf16 v[4:7], v[150:153], v[244:247], v[4:7]
	v_mfma_f32_16x16x32_bf16 v[48:51], v[158:161], v[232:235], v[48:51]
	v_mfma_f32_16x16x32_bf16 v[32:35], v[158:161], v[236:239], v[32:35]
	v_mfma_f32_16x16x32_bf16 v[16:19], v[158:161], v[240:243], v[16:19]
	v_mfma_f32_16x16x32_bf16 v[0:3], v[158:161], v[244:247], v[0:3]
	s_waitcnt vmcnt(8)
	s_barrier
	v_add_u32_e32 v112, 0x8000, v139
	v_or_b32_e32 v141, 0x8000, v140
	ds_read_b128 v[130:133], v141
	ds_read_b128 v[134:137], v141 offset:1024
	ds_read_b128 v[142:145], v141 offset:2048
	ds_read_b128 v[146:149], v141 offset:3072
	ds_read_b128 v[150:153], v112
	ds_read_b128 v[158:161], v112 offset:1024
	ds_read_b128 v[162:165], v112 offset:2048
	ds_read_b128 v[166:169], v112 offset:3072
	v_add_u32_e32 v141, 0x10000, v139
	s_waitcnt lgkmcnt(0)
	v_or_b32_e32 v154, 0x10000, v140
	v_mfma_f32_16x16x32_bf16 v[126:129], v[130:133], v[150:153], v[126:129]
	v_add_u32_e32 v139, 0x18000, v139
	s_lshl_b32 s8, s6, 8
	v_and_b32_e32 v170, 15, v138
	v_mfma_f32_16x16x32_bf16 v[122:125], v[134:137], v[150:153], v[122:125]
	s_and_b32 s18, s8, 0xffffc000
	s_ashr_i32 s7, s6, 1
	s_and_b32 s7, s7, 0xffffff80
	v_mfma_f32_16x16x32_bf16 v[118:121], v[142:145], v[150:153], v[118:121]
	s_and_b32 s6, s6, 0xc0
	s_add_i32 s8, s4, s7
	s_or_b32 s4, s5, s6
	v_mfma_f32_16x16x32_bf16 v[114:117], v[146:149], v[150:153], v[114:117]
	s_ashr_i32 s10, s4, 6
	s_ashr_i32 s11, s10, 31
	v_mfma_f32_16x16x32_bf16 v[108:111], v[130:133], v[158:161], v[108:111]
	v_mfma_f32_16x16x32_bf16 v[104:107], v[134:137], v[158:161], v[104:107]
	v_mfma_f32_16x16x32_bf16 v[100:103], v[142:145], v[158:161], v[100:103]
	v_mfma_f32_16x16x32_bf16 v[96:99], v[146:149], v[158:161], v[96:99]
	v_mfma_f32_16x16x32_bf16 v[92:95], v[130:133], v[162:165], v[92:95]
	v_mfma_f32_16x16x32_bf16 v[88:91], v[134:137], v[162:165], v[88:91]
	v_mfma_f32_16x16x32_bf16 v[84:87], v[142:145], v[162:165], v[84:87]
	v_mfma_f32_16x16x32_bf16 v[80:83], v[146:149], v[162:165], v[80:83]
	v_mfma_f32_16x16x32_bf16 v[76:79], v[130:133], v[166:169], v[76:79]
	v_mfma_f32_16x16x32_bf16 v[72:75], v[134:137], v[166:169], v[72:75]
	v_mfma_f32_16x16x32_bf16 v[68:71], v[142:145], v[166:169], v[68:71]
	v_mfma_f32_16x16x32_bf16 v[64:67], v[146:149], v[166:169], v[64:67]
	ds_read_b128 v[150:153], v112 offset:4096
	ds_read_b128 v[158:161], v112 offset:5120
	ds_read_b128 v[162:165], v112 offset:6144
	ds_read_b128 v[166:169], v112 offset:7168
	s_waitcnt lgkmcnt(0)
	s_waitcnt vmcnt(4)
	s_barrier
	v_mfma_f32_16x16x32_bf16 v[60:63], v[130:133], v[150:153], v[60:63]
	v_and_b32_e32 v112, 63, v138
	v_mfma_f32_16x16x32_bf16 v[56:59], v[134:137], v[150:153], v[56:59]
	v_mfma_f32_16x16x32_bf16 v[52:55], v[142:145], v[150:153], v[52:55]
	v_mfma_f32_16x16x32_bf16 v[48:51], v[146:149], v[150:153], v[48:51]
	v_mfma_f32_16x16x32_bf16 v[44:47], v[130:133], v[158:161], v[44:47]
	v_mfma_f32_16x16x32_bf16 v[40:43], v[134:137], v[158:161], v[40:43]
	v_mfma_f32_16x16x32_bf16 v[36:39], v[142:145], v[158:161], v[36:39]
	v_mfma_f32_16x16x32_bf16 v[32:35], v[146:149], v[158:161], v[32:35]
	v_mfma_f32_16x16x32_bf16 v[28:31], v[130:133], v[162:165], v[28:31]
	v_mfma_f32_16x16x32_bf16 v[24:27], v[134:137], v[162:165], v[24:27]
	v_mfma_f32_16x16x32_bf16 v[20:23], v[142:145], v[162:165], v[20:23]
	v_mfma_f32_16x16x32_bf16 v[16:19], v[146:149], v[162:165], v[16:19]
	v_mfma_f32_16x16x32_bf16 v[12:15], v[130:133], v[166:169], v[12:15]
	v_mfma_f32_16x16x32_bf16 v[8:11], v[134:137], v[166:169], v[8:11]
	v_mfma_f32_16x16x32_bf16 v[4:7], v[142:145], v[166:169], v[4:7]
	v_mfma_f32_16x16x32_bf16 v[0:3], v[146:149], v[166:169], v[0:3]
	ds_read_b128 v[130:133], v154
	ds_read_b128 v[134:137], v154 offset:1024
	ds_read_b128 v[142:145], v154 offset:2048
	ds_read_b128 v[146:149], v154 offset:3072
	ds_read_b128 v[150:153], v141
	ds_read_b128 v[158:161], v141 offset:1024
	ds_read_b128 v[162:165], v141 offset:2048
	ds_read_b128 v[166:169], v141 offset:3072
	s_nop 0
	s_waitcnt lgkmcnt(0)
	s_nop 0
	v_mfma_f32_16x16x32_bf16 v[126:129], v[130:133], v[150:153], v[126:129]
	v_mfma_f32_16x16x32_bf16 v[122:125], v[134:137], v[150:153], v[122:125]
	v_mfma_f32_16x16x32_bf16 v[118:121], v[142:145], v[150:153], v[118:121]
	v_mfma_f32_16x16x32_bf16 v[114:117], v[146:149], v[150:153], v[114:117]
	v_mfma_f32_16x16x32_bf16 v[108:111], v[130:133], v[158:161], v[108:111]
	v_mfma_f32_16x16x32_bf16 v[104:107], v[134:137], v[158:161], v[104:107]
	v_mfma_f32_16x16x32_bf16 v[100:103], v[142:145], v[158:161], v[100:103]
	v_mfma_f32_16x16x32_bf16 v[150:153], v[146:149], v[158:161], v[96:99]
	v_mfma_f32_16x16x32_bf16 v[92:95], v[130:133], v[162:165], v[92:95]
	v_mfma_f32_16x16x32_bf16 v[88:91], v[134:137], v[162:165], v[88:91]
	v_mfma_f32_16x16x32_bf16 v[84:87], v[142:145], v[162:165], v[84:87]
	v_mfma_f32_16x16x32_bf16 v[80:83], v[146:149], v[162:165], v[80:83]
	v_mfma_f32_16x16x32_bf16 v[76:79], v[130:133], v[166:169], v[76:79]
	v_mfma_f32_16x16x32_bf16 v[72:75], v[134:137], v[166:169], v[72:75]
	v_mfma_f32_16x16x32_bf16 v[68:71], v[142:145], v[166:169], v[68:71]
	v_mfma_f32_16x16x32_bf16 v[64:67], v[146:149], v[166:169], v[64:67]
	ds_read_b128 v[96:99], v141 offset:4096
	ds_read_b128 v[158:161], v141 offset:5120
	ds_read_b128 v[162:165], v141 offset:6144
	ds_read_b128 v[166:169], v141 offset:7168
	s_waitcnt lgkmcnt(0)
	s_waitcnt vmcnt(0)
	s_barrier
	v_mfma_f32_16x16x32_bf16 v[60:63], v[130:133], v[96:99], v[60:63]
	v_mfma_f32_16x16x32_bf16 v[56:59], v[134:137], v[96:99], v[56:59]
	v_mfma_f32_16x16x32_bf16 v[52:55], v[142:145], v[96:99], v[52:55]
	v_mfma_f32_16x16x32_bf16 v[48:51], v[146:149], v[96:99], v[48:51]
	v_mfma_f32_16x16x32_bf16 v[44:47], v[130:133], v[158:161], v[44:47]
	v_mfma_f32_16x16x32_bf16 v[40:43], v[134:137], v[158:161], v[40:43]
	v_mfma_f32_16x16x32_bf16 v[36:39], v[142:145], v[158:161], v[36:39]
	v_mfma_f32_16x16x32_bf16 v[32:35], v[146:149], v[158:161], v[32:35]
	v_mfma_f32_16x16x32_bf16 v[28:31], v[130:133], v[162:165], v[28:31]
	v_mfma_f32_16x16x32_bf16 v[24:27], v[134:137], v[162:165], v[24:27]
	v_mfma_f32_16x16x32_bf16 v[20:23], v[142:145], v[162:165], v[20:23]
	v_mfma_f32_16x16x32_bf16 v[16:19], v[146:149], v[162:165], v[16:19]
	v_mfma_f32_16x16x32_bf16 v[12:15], v[130:133], v[166:169], v[12:15]
	v_mfma_f32_16x16x32_bf16 v[8:11], v[134:137], v[166:169], v[8:11]
	v_mfma_f32_16x16x32_bf16 v[4:7], v[142:145], v[166:169], v[4:7]
	v_mfma_f32_16x16x32_bf16 v[0:3], v[146:149], v[166:169], v[0:3]
	v_or_b32_e32 v148, 0x18000, v140
	ds_read_b128 v[130:133], v148
	ds_read_b128 v[134:137], v148 offset:1024
	ds_read_b128 v[140:143], v148 offset:2048
	ds_read_b128 v[144:147], v148 offset:3072
	ds_read_b128 v[96:99], v139
	ds_read_b128 v[158:161], v139 offset:1024
	ds_read_b128 v[162:165], v139 offset:2048
	ds_read_b128 v[166:169], v139 offset:3072
	s_nop 0
	s_waitcnt lgkmcnt(0)
	s_nop 0
	v_mfma_f32_16x16x32_bf16 v[126:129], v[130:133], v[96:99], v[126:129]
	v_mfma_f32_16x16x32_bf16 v[174:177], v[134:137], v[96:99], v[122:125]
	v_mfma_f32_16x16x32_bf16 v[182:185], v[140:143], v[96:99], v[118:121]
	v_mfma_f32_16x16x32_bf16 v[114:117], v[144:147], v[96:99], v[114:117]
	v_mfma_f32_16x16x32_bf16 v[96:99], v[140:143], v[158:161], v[100:103]
	v_mfma_f32_16x16x32_bf16 v[100:103], v[144:147], v[158:161], v[150:153]
	ds_read_b128 v[118:121], v139 offset:4096
	ds_read_b128 v[122:125], v139 offset:5120
	ds_read_b128 v[148:151], v139 offset:6144
	ds_read_b128 v[152:155], v139 offset:7168
	s_waitcnt lgkmcnt(0)
	s_barrier
	v_mfma_f32_16x16x32_bf16 v[60:63], v[130:133], v[118:121], v[60:63]
	v_mfma_f32_16x16x32_bf16 v[56:59], v[134:137], v[118:121], v[56:59]
	v_mfma_f32_16x16x32_bf16 v[52:55], v[140:143], v[118:121], v[52:55]
	v_mfma_f32_16x16x32_bf16 v[48:51], v[144:147], v[118:121], v[48:51]
	v_bfe_u32 v119, v138, 5, 1
	v_lshrrev_b32_e32 v121, 1, v138
	v_lshlrev_b32_e32 v118, 7, v170
	v_mfma_f32_16x16x32_bf16 v[44:47], v[130:133], v[122:125], v[44:47]
	v_and_b32_e32 v121, 8, v121
	v_and_b32_e32 v120, 7, v138
	v_mfma_f32_16x16x32_bf16 v[40:43], v[134:137], v[122:125], v[40:43]
	v_mfma_f32_16x16x32_bf16 v[36:39], v[140:143], v[122:125], v[36:39]
	v_mfma_f32_16x16x32_bf16 v[32:35], v[144:147], v[122:125], v[32:35]
	v_mul_f32_e32 v125, v127, v127
	v_bitop3_b32 v124, v119, v138, 7 bitop3:0x78
	v_or3_b32 v123, s18, v118, v121
	v_fmac_f32_e32 v125, v126, v126
	v_lshlrev_b32_e32 v124, 4, v124
	v_fmac_f32_e32 v125, v128, v128
	v_cvt_pk_bf16_f32 v126, v126, v127
	v_cvt_pk_bf16_f32 v127, v128, v129
	v_or_b32_e32 v128, v123, v124
	s_waitcnt vmcnt(0)
	ds_write_b64 v128, v[126:127]
	v_mul_f32_e32 v126, v175, v175
	v_fmac_f32_e32 v126, v174, v174
	v_fmac_f32_e32 v126, v176, v176
	v_fmac_f32_e32 v125, v129, v129
	v_fmac_f32_e32 v126, v177, v177
	v_add_f32_e32 v125, v125, v126
	v_bitop3_b32 v126, v119, v120, 2 bitop3:0x36
	v_lshlrev_b32_e32 v126, 4, v126
	v_cvt_pk_bf16_f32 v128, v174, v175
	v_cvt_pk_bf16_f32 v129, v176, v177
	v_or_b32_e32 v127, v123, v126
	ds_write_b64 v127, v[128:129]
	v_mul_f32_e32 v127, v183, v183
	v_fmac_f32_e32 v127, v182, v182
	v_fmac_f32_e32 v127, v184, v184
	v_fmac_f32_e32 v127, v185, v185
	v_add_f32_e32 v127, v125, v127
	v_bitop3_b32 v125, v119, v120, 4 bitop3:0x36
	v_lshlrev_b32_e32 v125, 4, v125
	v_mfma_f32_16x16x32_bf16 v[108:111], v[130:133], v[158:161], v[108:111]
	v_cvt_pk_bf16_f32 v128, v182, v183
	v_cvt_pk_bf16_f32 v129, v184, v185
	v_and_b32_e32 v121, 64, v172
	v_mfma_f32_16x16x32_bf16 v[92:95], v[130:133], v[162:165], v[92:95]
	v_xor_b32_e32 v118, 16, v172
	v_add_u32_e32 v122, 64, v121
	v_cmp_lt_i32_e32 vcc, v118, v122
	v_mfma_f32_16x16x32_bf16 v[76:79], v[130:133], v[166:169], v[76:79]
	s_nop 0
	v_cndmask_b32_e32 v118, v172, v118, vcc
	v_lshlrev_b32_e32 v121, 2, v118
	v_mfma_f32_16x16x32_bf16 v[28:31], v[130:133], v[148:151], v[28:31]
	v_xor_b32_e32 v118, 32, v172
	v_cmp_lt_i32_e32 vcc, v118, v122
	v_mfma_f32_16x16x32_bf16 v[12:15], v[130:133], v[152:155], v[12:15]
	v_or_b32_e32 v130, v123, v125
	ds_write_b64 v130, v[128:129]
	v_mul_f32_e32 v128, v115, v115
	v_fmac_f32_e32 v128, v114, v114
	v_fmac_f32_e32 v128, v116, v116
	v_fmac_f32_e32 v128, v117, v117
	v_add_f32_e32 v127, v127, v128
	v_cvt_pk_bf16_f32 v128, v114, v115
	v_bitop3_b32 v114, v119, v120, 6 bitop3:0x36
	v_lshlrev_b32_e32 v114, 4, v114
	v_cvt_pk_bf16_f32 v129, v116, v117
	v_or_b32_e32 v115, v123, v114
	ds_write_b64 v115, v[128:129]
	ds_bpermute_b32 v115, v121, v127
	v_cndmask_b32_e32 v118, v172, v118, vcc
	v_lshlrev_b32_e32 v122, 2, v118
	v_mfma_f32_16x16x32_bf16 v[104:107], v[134:137], v[158:161], v[104:107]
	v_cmp_gt_u32_e32 vcc, 16, v112
	s_waitcnt lgkmcnt(0)
	v_add_f32_e32 v115, v127, v115
	ds_bpermute_b32 v116, v122, v115
	v_mfma_f32_16x16x32_bf16 v[88:91], v[134:137], v[162:165], v[88:91]
	v_or_b32_e32 v118, s8, v170
	v_mfma_f32_16x16x32_bf16 v[84:87], v[140:143], v[162:165], v[84:87]
	v_mfma_f32_16x16x32_bf16 v[80:83], v[144:147], v[162:165], v[80:83]
	v_mfma_f32_16x16x32_bf16 v[72:75], v[134:137], v[166:169], v[72:75]
	v_mfma_f32_16x16x32_bf16 v[68:71], v[140:143], v[166:169], v[68:71]
	v_mfma_f32_16x16x32_bf16 v[64:67], v[144:147], v[166:169], v[64:67]
	v_mfma_f32_16x16x32_bf16 v[24:27], v[134:137], v[148:151], v[24:27]
	v_mfma_f32_16x16x32_bf16 v[20:23], v[140:143], v[148:151], v[20:23]
	v_mfma_f32_16x16x32_bf16 v[16:19], v[144:147], v[148:151], v[16:19]
	v_mfma_f32_16x16x32_bf16 v[8:11], v[134:137], v[152:155], v[8:11]
	v_mfma_f32_16x16x32_bf16 v[4:7], v[140:143], v[152:155], v[4:7]
	v_mfma_f32_16x16x32_bf16 v[0:3], v[144:147], v[152:155], v[0:3]
	s_and_saveexec_b64 s[6:7], vcc
	s_cbranch_execz .LBB0_545
	v_ashrrev_i32_e32 v119, 31, v118
	s_waitcnt lgkmcnt(0)
	v_add_f32_e32 v115, v115, v116
	v_lshlrev_b64 v[116:117], 6, v[118:119]
	v_lshl_add_u64 v[116:117], s[44:45], 0, v[116:117]
	v_lshl_add_u64 v[116:117], s[10:11], 2, v[116:117]
	global_store_dword v[116:117], v115, off

.Lgsk2_loop:
	s_add_i32 s8, s5, 0xfffe8000
	s_and_b32 s9, s5, 0x18000
	s_waitcnt vmcnt(8) lgkmcnt(0)
	s_barrier
	s_and_b32 s8, s8, 0x18000
	s_add_i32 s9, s4, s9
	v_add_u32_e32 v128, s8, v160
	v_or_b32_e32 v170, s8, v161
	s_add_i32 s11, s9, 0x400
	s_add_i32 s10, s9, 0x800
	s_add_i32 s8, s9, 0xc00
	s_add_i32 s5, s5, 0x8000
	s_cmp_eq_u32 s5, 0x100000
	ds_read_b128 v[182:185], v128
	ds_read_b128 v[186:189], v128 offset:1024
	ds_read_b128 v[190:193], v128 offset:2048
	ds_read_b128 v[194:197], v128 offset:3072
	v_mfma_f32_16x16x32_bf16 v[60:63], v[162:165], v[232:235], v[60:63]
	v_mfma_f32_16x16x32_bf16 v[44:47], v[162:165], v[236:239], v[44:47]
	v_mfma_f32_16x16x32_bf16 v[28:31], v[162:165], v[240:243], v[28:31]
	v_mfma_f32_16x16x32_bf16 v[12:15], v[162:165], v[244:247], v[12:15]
	v_mfma_f32_16x16x32_bf16 v[56:59], v[166:169], v[232:235], v[56:59]
	ds_read_b128 v[162:165], v170
	v_mfma_f32_16x16x32_bf16 v[40:43], v[166:169], v[236:239], v[40:43]
	v_mfma_f32_16x16x32_bf16 v[24:27], v[166:169], v[240:243], v[24:27]
	v_mfma_f32_16x16x32_bf16 v[8:11], v[166:169], v[244:247], v[8:11]
	v_mfma_f32_16x16x32_bf16 v[52:55], v[174:177], v[232:235], v[52:55]
	ds_read_b128 v[166:169], v170 offset:1024
	v_mfma_f32_16x16x32_bf16 v[36:39], v[174:177], v[236:239], v[36:39]
	v_mfma_f32_16x16x32_bf16 v[20:23], v[174:177], v[240:243], v[20:23]
	v_mfma_f32_16x16x32_bf16 v[4:7], v[174:177], v[244:247], v[4:7]
	v_mfma_f32_16x16x32_bf16 v[48:51], v[178:181], v[232:235], v[48:51]
	ds_read_b128 v[174:177], v170 offset:2048
	v_mfma_f32_16x16x32_bf16 v[32:35], v[178:181], v[236:239], v[32:35]
	v_mfma_f32_16x16x32_bf16 v[16:19], v[178:181], v[240:243], v[16:19]
	v_mfma_f32_16x16x32_bf16 v[0:3], v[178:181], v[244:247], v[0:3]
	s_waitcnt lgkmcnt(2)
	v_mfma_f32_16x16x32_bf16 v[124:127], v[162:165], v[182:185], v[124:127]
	ds_read_b128 v[178:181], v170 offset:3072
	v_mfma_f32_16x16x32_bf16 v[108:111], v[162:165], v[186:189], v[108:111]
	ds_read_b128 v[232:235], v128 offset:4096
	ds_read_b128 v[236:239], v128 offset:5120
	v_mfma_f32_16x16x32_bf16 v[92:95], v[162:165], v[190:193], v[92:95]
	ds_read_b128 v[240:243], v128 offset:6144
	ds_read_b128 v[244:247], v128 offset:7168
	s_mov_b32 m0, s9
	v_mfma_f32_16x16x32_bf16 v[76:79], v[162:165], v[194:197], v[76:79]
	global_load_lds_dwordx4 v[136:137], off
	v_lshl_add_u64 v[136:137], v[136:137], 0, 64
	s_waitcnt lgkmcnt(6)
	v_mfma_f32_16x16x32_bf16 v[120:123], v[166:169], v[182:185], v[120:123]
	v_mfma_f32_16x16x32_bf16 v[104:107], v[166:169], v[186:189], v[104:107]
	v_mfma_f32_16x16x32_bf16 v[88:91], v[166:169], v[190:193], v[88:91]
	s_mov_b32 m0, s11
	v_mfma_f32_16x16x32_bf16 v[72:75], v[166:169], v[194:197], v[72:75]
	global_load_lds_dwordx4 v[134:135], off
	v_lshl_add_u64 v[134:135], v[134:135], 0, 64
	s_waitcnt lgkmcnt(5)
	v_mfma_f32_16x16x32_bf16 v[116:119], v[174:177], v[182:185], v[116:119]
	v_mfma_f32_16x16x32_bf16 v[100:103], v[174:177], v[186:189], v[100:103]
	v_mfma_f32_16x16x32_bf16 v[84:87], v[174:177], v[190:193], v[84:87]
	s_mov_b32 m0, s10
	v_mfma_f32_16x16x32_bf16 v[68:71], v[174:177], v[194:197], v[68:71]
	global_load_lds_dwordx4 v[132:133], off
	v_lshl_add_u64 v[132:133], v[132:133], 0, 64
	s_waitcnt lgkmcnt(4)
	v_mfma_f32_16x16x32_bf16 v[112:115], v[178:181], v[182:185], v[112:115]
	v_mfma_f32_16x16x32_bf16 v[96:99], v[178:181], v[186:189], v[96:99]
	v_mfma_f32_16x16x32_bf16 v[80:83], v[178:181], v[190:193], v[80:83]
	s_mov_b32 m0, s8
	v_mfma_f32_16x16x32_bf16 v[64:67], v[178:181], v[194:197], v[64:67]
	global_load_lds_dwordx4 v[130:131], off
	v_lshl_add_u64 v[130:131], v[130:131], 0, 64
	s_cbranch_scc0 .Lgsk2_loop
	s_waitcnt lgkmcnt(0)
	v_mfma_f32_16x16x32_bf16 v[60:63], v[162:165], v[232:235], v[60:63]
	v_mfma_f32_16x16x32_bf16 v[44:47], v[162:165], v[236:239], v[44:47]
	v_mfma_f32_16x16x32_bf16 v[28:31], v[162:165], v[240:243], v[28:31]
	v_mfma_f32_16x16x32_bf16 v[12:15], v[162:165], v[244:247], v[12:15]
	v_mfma_f32_16x16x32_bf16 v[56:59], v[166:169], v[232:235], v[56:59]
	v_mfma_f32_16x16x32_bf16 v[40:43], v[166:169], v[236:239], v[40:43]
	v_mfma_f32_16x16x32_bf16 v[24:27], v[166:169], v[240:243], v[24:27]
	v_mfma_f32_16x16x32_bf16 v[8:11], v[166:169], v[244:247], v[8:11]
	v_mfma_f32_16x16x32_bf16 v[52:55], v[174:177], v[232:235], v[52:55]
	v_mfma_f32_16x16x32_bf16 v[36:39], v[174:177], v[236:239], v[36:39]
	v_mfma_f32_16x16x32_bf16 v[20:23], v[174:177], v[240:243], v[20:23]
	v_mfma_f32_16x16x32_bf16 v[4:7], v[174:177], v[244:247], v[4:7]
	v_mfma_f32_16x16x32_bf16 v[48:51], v[178:181], v[232:235], v[48:51]
	v_mfma_f32_16x16x32_bf16 v[32:35], v[178:181], v[236:239], v[32:35]
	v_mfma_f32_16x16x32_bf16 v[16:19], v[178:181], v[240:243], v[16:19]
	v_mfma_f32_16x16x32_bf16 v[0:3], v[178:181], v[244:247], v[0:3]
	s_waitcnt vmcnt(8)
	s_barrier
	v_add_u32_e32 v128, 0x8000, v160
	v_or_b32_e32 v170, 0x8000, v161
	ds_read_b128 v[130:133], v170
	ds_read_b128 v[134:137], v170 offset:1024
	ds_read_b128 v[162:165], v170 offset:2048
	ds_read_b128 v[166:169], v170 offset:3072
	ds_read_b128 v[174:177], v128
	ds_read_b128 v[178:181], v128 offset:1024
	ds_read_b128 v[182:185], v128 offset:2048
	ds_read_b128 v[186:189], v128 offset:3072
	v_or_b32_e32 v170, 0x10000, v161
	s_waitcnt lgkmcnt(0)
	v_or_b32_e32 v173, 0x18000, v161
	v_mfma_f32_16x16x32_bf16 v[124:127], v[130:133], v[174:177], v[124:127]
	s_cmp_eq_u32 s13, 2
	s_cselect_b64 s[8:9], -1, 0
	s_cmp_eq_u32 s13, 3
	v_mfma_f32_16x16x32_bf16 v[120:123], v[134:137], v[174:177], v[120:123]
	s_cselect_b64 s[4:5], -1, 0
	s_and_b64 vcc, exec, s[4:5]
	v_mfma_f32_16x16x32_bf16 v[116:119], v[162:165], v[174:177], v[116:119]
	v_mfma_f32_16x16x32_bf16 v[112:115], v[166:169], v[174:177], v[112:115]
	v_mfma_f32_16x16x32_bf16 v[108:111], v[130:133], v[178:181], v[108:111]
	v_mfma_f32_16x16x32_bf16 v[104:107], v[134:137], v[178:181], v[104:107]
	v_mfma_f32_16x16x32_bf16 v[100:103], v[162:165], v[178:181], v[100:103]
	v_mfma_f32_16x16x32_bf16 v[96:99], v[166:169], v[178:181], v[96:99]
	v_mfma_f32_16x16x32_bf16 v[92:95], v[130:133], v[182:185], v[92:95]
	v_mfma_f32_16x16x32_bf16 v[88:91], v[134:137], v[182:185], v[88:91]
	v_mfma_f32_16x16x32_bf16 v[84:87], v[162:165], v[182:185], v[84:87]
	v_mfma_f32_16x16x32_bf16 v[80:83], v[166:169], v[182:185], v[80:83]
	v_mfma_f32_16x16x32_bf16 v[76:79], v[130:133], v[186:189], v[76:79]
	v_mfma_f32_16x16x32_bf16 v[72:75], v[134:137], v[186:189], v[72:75]
	v_mfma_f32_16x16x32_bf16 v[68:71], v[162:165], v[186:189], v[68:71]
	v_mfma_f32_16x16x32_bf16 v[64:67], v[166:169], v[186:189], v[64:67]
	ds_read_b128 v[174:177], v128 offset:4096
	ds_read_b128 v[178:181], v128 offset:5120
	ds_read_b128 v[182:185], v128 offset:6144
	ds_read_b128 v[186:189], v128 offset:7168
	s_waitcnt lgkmcnt(0)
	s_waitcnt vmcnt(4)
	s_barrier
	v_mfma_f32_16x16x32_bf16 v[60:63], v[130:133], v[174:177], v[60:63]
	v_add_u32_e32 v128, 0x10000, v160
	v_mfma_f32_16x16x32_bf16 v[56:59], v[134:137], v[174:177], v[56:59]
	v_mfma_f32_16x16x32_bf16 v[52:55], v[162:165], v[174:177], v[52:55]
	v_mfma_f32_16x16x32_bf16 v[48:51], v[166:169], v[174:177], v[48:51]
	v_mfma_f32_16x16x32_bf16 v[44:47], v[130:133], v[178:181], v[44:47]
	v_mfma_f32_16x16x32_bf16 v[40:43], v[134:137], v[178:181], v[40:43]
	v_mfma_f32_16x16x32_bf16 v[36:39], v[162:165], v[178:181], v[36:39]
	v_mfma_f32_16x16x32_bf16 v[32:35], v[166:169], v[178:181], v[32:35]
	v_mfma_f32_16x16x32_bf16 v[28:31], v[130:133], v[182:185], v[28:31]
	v_mfma_f32_16x16x32_bf16 v[24:27], v[134:137], v[182:185], v[24:27]
	v_mfma_f32_16x16x32_bf16 v[20:23], v[162:165], v[182:185], v[20:23]
	v_mfma_f32_16x16x32_bf16 v[16:19], v[166:169], v[182:185], v[16:19]
	v_mfma_f32_16x16x32_bf16 v[12:15], v[130:133], v[186:189], v[12:15]
	v_mfma_f32_16x16x32_bf16 v[8:11], v[134:137], v[186:189], v[8:11]
	v_mfma_f32_16x16x32_bf16 v[4:7], v[162:165], v[186:189], v[4:7]
	v_mfma_f32_16x16x32_bf16 v[0:3], v[166:169], v[186:189], v[0:3]
	ds_read_b128 v[130:133], v170
	ds_read_b128 v[134:137], v170 offset:1024
	ds_read_b128 v[162:165], v170 offset:2048
	ds_read_b128 v[166:169], v170 offset:3072
	ds_read_b128 v[174:177], v128
	ds_read_b128 v[178:181], v128 offset:1024
	ds_read_b128 v[182:185], v128 offset:2048
	ds_read_b128 v[186:189], v128 offset:3072
	s_nop 0
	s_waitcnt lgkmcnt(0)
	s_nop 0
	v_mfma_f32_16x16x32_bf16 v[124:127], v[130:133], v[174:177], v[124:127]
	v_mfma_f32_16x16x32_bf16 v[120:123], v[134:137], v[174:177], v[120:123]
	v_mfma_f32_16x16x32_bf16 v[116:119], v[162:165], v[174:177], v[116:119]
	v_mfma_f32_16x16x32_bf16 v[112:115], v[166:169], v[174:177], v[112:115]
	v_mfma_f32_16x16x32_bf16 v[108:111], v[130:133], v[178:181], v[108:111]
	v_mfma_f32_16x16x32_bf16 v[104:107], v[134:137], v[178:181], v[104:107]
	v_mfma_f32_16x16x32_bf16 v[100:103], v[162:165], v[178:181], v[100:103]
	v_mfma_f32_16x16x32_bf16 v[96:99], v[166:169], v[178:181], v[96:99]
	v_mfma_f32_16x16x32_bf16 v[92:95], v[130:133], v[182:185], v[92:95]
	v_mfma_f32_16x16x32_bf16 v[88:91], v[134:137], v[182:185], v[88:91]
	v_mfma_f32_16x16x32_bf16 v[84:87], v[162:165], v[182:185], v[84:87]
	v_mfma_f32_16x16x32_bf16 v[80:83], v[166:169], v[182:185], v[80:83]
	v_mfma_f32_16x16x32_bf16 v[76:79], v[130:133], v[186:189], v[76:79]
	v_mfma_f32_16x16x32_bf16 v[72:75], v[134:137], v[186:189], v[72:75]
	v_mfma_f32_16x16x32_bf16 v[68:71], v[162:165], v[186:189], v[68:71]
	v_mfma_f32_16x16x32_bf16 v[64:67], v[166:169], v[186:189], v[64:67]
	ds_read_b128 v[174:177], v128 offset:4096
	ds_read_b128 v[178:181], v128 offset:5120
	ds_read_b128 v[182:185], v128 offset:6144
	ds_read_b128 v[186:189], v128 offset:7168
	s_waitcnt lgkmcnt(0)
	s_waitcnt vmcnt(0)
	s_barrier
	v_mfma_f32_16x16x32_bf16 v[60:63], v[130:133], v[174:177], v[60:63]
	v_add_u32_e32 v128, 0x18000, v160
	v_mfma_f32_16x16x32_bf16 v[56:59], v[134:137], v[174:177], v[56:59]
	v_mfma_f32_16x16x32_bf16 v[52:55], v[162:165], v[174:177], v[52:55]
	v_mfma_f32_16x16x32_bf16 v[48:51], v[166:169], v[174:177], v[48:51]
	v_mfma_f32_16x16x32_bf16 v[44:47], v[130:133], v[178:181], v[44:47]
	v_mfma_f32_16x16x32_bf16 v[40:43], v[134:137], v[178:181], v[40:43]
	v_mfma_f32_16x16x32_bf16 v[36:39], v[162:165], v[178:181], v[36:39]
	v_mfma_f32_16x16x32_bf16 v[32:35], v[166:169], v[178:181], v[32:35]
	v_mfma_f32_16x16x32_bf16 v[28:31], v[130:133], v[182:185], v[28:31]
	v_mfma_f32_16x16x32_bf16 v[24:27], v[134:137], v[182:185], v[24:27]
	v_mfma_f32_16x16x32_bf16 v[20:23], v[162:165], v[182:185], v[20:23]
	v_mfma_f32_16x16x32_bf16 v[16:19], v[166:169], v[182:185], v[16:19]
	v_mfma_f32_16x16x32_bf16 v[12:15], v[130:133], v[186:189], v[12:15]
	v_mfma_f32_16x16x32_bf16 v[8:11], v[134:137], v[186:189], v[8:11]
	v_mfma_f32_16x16x32_bf16 v[4:7], v[162:165], v[186:189], v[4:7]
	v_mfma_f32_16x16x32_bf16 v[0:3], v[166:169], v[186:189], v[0:3]
	ds_read_b128 v[130:133], v173
	ds_read_b128 v[134:137], v173 offset:1024
	ds_read_b128 v[160:163], v173 offset:2048
	ds_read_b128 v[164:167], v173 offset:3072
	ds_read_b128 v[168:171], v128
	ds_read_b128 v[174:177], v128 offset:1024
	ds_read_b128 v[178:181], v128 offset:2048
	ds_read_b128 v[182:185], v128 offset:3072
	s_nop 0
	s_waitcnt lgkmcnt(0)
	s_nop 0
	v_mfma_f32_16x16x32_bf16 v[186:189], v[130:133], v[168:171], v[124:127]
	v_mfma_f32_16x16x32_bf16 v[120:123], v[134:137], v[168:171], v[120:123]
	v_mfma_f32_16x16x32_bf16 v[116:119], v[160:163], v[168:171], v[116:119]
	v_mfma_f32_16x16x32_bf16 v[112:115], v[164:167], v[168:171], v[112:115]
	v_mfma_f32_16x16x32_bf16 v[108:111], v[130:133], v[174:177], v[108:111]
	v_mfma_f32_16x16x32_bf16 v[104:107], v[134:137], v[174:177], v[104:107]
	v_mfma_f32_16x16x32_bf16 v[100:103], v[160:163], v[174:177], v[100:103]
	v_mfma_f32_16x16x32_bf16 v[96:99], v[164:167], v[174:177], v[96:99]
	v_mfma_f32_16x16x32_bf16 v[92:95], v[130:133], v[178:181], v[92:95]
	v_mfma_f32_16x16x32_bf16 v[88:91], v[134:137], v[178:181], v[88:91]
	v_mfma_f32_16x16x32_bf16 v[84:87], v[160:163], v[178:181], v[84:87]
	v_mfma_f32_16x16x32_bf16 v[80:83], v[164:167], v[178:181], v[80:83]
	ds_read_b128 v[124:127], v128 offset:4096
	ds_read_b128 v[168:171], v128 offset:5120
	ds_read_b128 v[174:177], v128 offset:6144
	ds_read_b128 v[178:181], v128 offset:7168
	s_waitcnt lgkmcnt(0)
	s_barrier
	v_mfma_f32_16x16x32_bf16 v[76:79], v[130:133], v[182:185], v[76:79]
	v_mfma_f32_16x16x32_bf16 v[72:75], v[134:137], v[182:185], v[72:75]
	v_mfma_f32_16x16x32_bf16 v[68:71], v[160:163], v[182:185], v[68:71]
	v_mfma_f32_16x16x32_bf16 v[64:67], v[164:167], v[182:185], v[64:67]
	v_mfma_f32_16x16x32_bf16 v[60:63], v[130:133], v[124:127], v[60:63]
	v_mfma_f32_16x16x32_bf16 v[56:59], v[134:137], v[124:127], v[56:59]
	v_mfma_f32_16x16x32_bf16 v[52:55], v[160:163], v[124:127], v[52:55]
	v_mfma_f32_16x16x32_bf16 v[48:51], v[164:167], v[124:127], v[48:51]
	v_mfma_f32_16x16x32_bf16 v[44:47], v[130:133], v[168:171], v[44:47]
	v_mfma_f32_16x16x32_bf16 v[40:43], v[134:137], v[168:171], v[40:43]
	v_mfma_f32_16x16x32_bf16 v[36:39], v[160:163], v[168:171], v[36:39]
	v_mfma_f32_16x16x32_bf16 v[32:35], v[164:167], v[168:171], v[32:35]
	v_mfma_f32_16x16x32_bf16 v[28:31], v[130:133], v[174:177], v[28:31]
	v_mfma_f32_16x16x32_bf16 v[24:27], v[134:137], v[174:177], v[24:27]
	v_mfma_f32_16x16x32_bf16 v[20:23], v[160:163], v[174:177], v[20:23]
	v_mfma_f32_16x16x32_bf16 v[16:19], v[164:167], v[174:177], v[16:19]
	v_mfma_f32_16x16x32_bf16 v[12:15], v[130:133], v[178:181], v[12:15]
	v_cndmask_b32_e64 v132, 1.0, v156, s[8:9]
	v_mul_f32_e32 v124, v132, v159
	v_pk_mul_f32 v[126:127], v[124:125], v[188:189] op_sel_hi:[0,1]
	v_mfma_f32_16x16x32_bf16 v[8:11], v[134:137], v[178:181], v[8:11]
	v_mul_f32_e64 v130, v124, v186
	v_mul_f32_e64 v131, v124, v187
	v_mfma_f32_16x16x32_bf16 v[4:7], v[160:163], v[178:181], v[4:7]
	v_mfma_f32_16x16x32_bf16 v[0:3], v[164:167], v[178:181], v[0:3]
	s_cbranch_vccz .LBB0_809
	v_mul_f32_e32 v125, 0xbfb8aa3b, v130
	v_exp_f32_e32 v125, v125
	v_mul_f32_e32 v133, 0xbfb8aa3b, v126
	v_mul_f32_e32 v128, 0xbfb8aa3b, v131
	v_exp_f32_e32 v128, v128
	v_add_f32_e32 v125, 1.0, v125
	v_rcp_f32_e32 v134, v125
	v_exp_f32_e32 v125, v133
	v_mul_f32_e32 v133, 0xbfb8aa3b, v127
	v_exp_f32_e32 v133, v133
	v_add_f32_e32 v128, 1.0, v128
	v_add_f32_e32 v125, 1.0, v125
	v_rcp_f32_e32 v136, v125
	v_add_f32_e32 v125, 1.0, v133
	v_rcp_f32_e32 v137, v125
	v_rcp_f32_e32 v135, v128
	v_pk_mul_f32 v[126:127], v[126:127], v[136:137]
	v_pk_mul_f32 v[130:131], v[130:131], v[134:135]

.Lgsk3_loop:
	s_add_i32 s8, s5, 0xfffe8000
	s_and_b32 s9, s5, 0x18000
	s_waitcnt vmcnt(8) lgkmcnt(0)
	s_barrier
	s_and_b32 s8, s8, 0x18000
	s_add_i32 s9, s4, s9
	v_add_u32_e32 v128, s8, v141
	v_or_b32_e32 v143, s8, v142
	s_add_i32 s11, s9, 0x400
	s_add_i32 s10, s9, 0x800
	s_add_i32 s8, s9, 0xc00
	s_add_i32 s5, s5, 0x8000
	s_cmp_eq_u32 s5, 0x100000
	ds_read_b128 v[174:177], v128
	ds_read_b128 v[178:181], v128 offset:1024
	ds_read_b128 v[182:185], v128 offset:2048
	ds_read_b128 v[186:189], v128 offset:3072
	v_mfma_f32_16x16x32_bf16 v[60:63], v[232:235], v[144:147], v[60:63]
	v_mfma_f32_16x16x32_bf16 v[44:47], v[236:239], v[144:147], v[44:47]
	v_mfma_f32_16x16x32_bf16 v[28:31], v[240:243], v[144:147], v[28:31]
	v_mfma_f32_16x16x32_bf16 v[12:15], v[244:247], v[144:147], v[12:15]
	v_mfma_f32_16x16x32_bf16 v[56:59], v[232:235], v[158:161], v[56:59]
	ds_read_b128 v[144:147], v143
	v_mfma_f32_16x16x32_bf16 v[40:43], v[236:239], v[158:161], v[40:43]
	v_mfma_f32_16x16x32_bf16 v[24:27], v[240:243], v[158:161], v[24:27]
	v_mfma_f32_16x16x32_bf16 v[8:11], v[244:247], v[158:161], v[8:11]
	v_mfma_f32_16x16x32_bf16 v[52:55], v[232:235], v[162:165], v[52:55]
	ds_read_b128 v[158:161], v143 offset:1024
	v_mfma_f32_16x16x32_bf16 v[36:39], v[236:239], v[162:165], v[36:39]
	v_mfma_f32_16x16x32_bf16 v[20:23], v[240:243], v[162:165], v[20:23]
	v_mfma_f32_16x16x32_bf16 v[4:7], v[244:247], v[162:165], v[4:7]
	v_mfma_f32_16x16x32_bf16 v[48:51], v[232:235], v[166:169], v[48:51]
	ds_read_b128 v[162:165], v143 offset:2048
	v_mfma_f32_16x16x32_bf16 v[32:35], v[236:239], v[166:169], v[32:35]
	v_mfma_f32_16x16x32_bf16 v[16:19], v[240:243], v[166:169], v[16:19]
	v_mfma_f32_16x16x32_bf16 v[0:3], v[244:247], v[166:169], v[0:3]
	s_waitcnt lgkmcnt(2)
	v_mfma_f32_16x16x32_bf16 v[124:127], v[174:177], v[144:147], v[124:127]
	ds_read_b128 v[166:169], v143 offset:3072
	v_mfma_f32_16x16x32_bf16 v[108:111], v[178:181], v[144:147], v[108:111]
	ds_read_b128 v[232:235], v128 offset:4096
	ds_read_b128 v[236:239], v128 offset:5120
	v_mfma_f32_16x16x32_bf16 v[92:95], v[182:185], v[144:147], v[92:95]
	ds_read_b128 v[240:243], v128 offset:6144
	ds_read_b128 v[244:247], v128 offset:7168
	s_mov_b32 m0, s9
	v_mfma_f32_16x16x32_bf16 v[76:79], v[186:189], v[144:147], v[76:79]
	global_load_lds_dwordx4 v[136:137], off
	v_lshl_add_u64 v[136:137], v[136:137], 0, 64
	s_waitcnt lgkmcnt(6)
	v_mfma_f32_16x16x32_bf16 v[120:123], v[174:177], v[158:161], v[120:123]
	v_mfma_f32_16x16x32_bf16 v[104:107], v[178:181], v[158:161], v[104:107]
	v_mfma_f32_16x16x32_bf16 v[88:91], v[182:185], v[158:161], v[88:91]
	s_mov_b32 m0, s11
	v_mfma_f32_16x16x32_bf16 v[72:75], v[186:189], v[158:161], v[72:75]
	global_load_lds_dwordx4 v[134:135], off
	v_lshl_add_u64 v[134:135], v[134:135], 0, 64
	s_waitcnt lgkmcnt(5)
	v_mfma_f32_16x16x32_bf16 v[116:119], v[174:177], v[162:165], v[116:119]
	v_mfma_f32_16x16x32_bf16 v[100:103], v[178:181], v[162:165], v[100:103]
	v_mfma_f32_16x16x32_bf16 v[84:87], v[182:185], v[162:165], v[84:87]
	s_mov_b32 m0, s10
	v_mfma_f32_16x16x32_bf16 v[68:71], v[186:189], v[162:165], v[68:71]
	global_load_lds_dwordx4 v[132:133], off
	v_lshl_add_u64 v[132:133], v[132:133], 0, 64
	s_waitcnt lgkmcnt(4)
	v_mfma_f32_16x16x32_bf16 v[112:115], v[174:177], v[166:169], v[112:115]
	v_mfma_f32_16x16x32_bf16 v[96:99], v[178:181], v[166:169], v[96:99]
	v_mfma_f32_16x16x32_bf16 v[80:83], v[182:185], v[166:169], v[80:83]
	s_mov_b32 m0, s8
	v_mfma_f32_16x16x32_bf16 v[64:67], v[186:189], v[166:169], v[64:67]
	global_load_lds_dwordx4 v[130:131], off
	v_lshl_add_u64 v[130:131], v[130:131], 0, 64
	s_cbranch_scc0 .Lgsk3_loop
	s_waitcnt lgkmcnt(0)
	v_mfma_f32_16x16x32_bf16 v[60:63], v[232:235], v[144:147], v[60:63]
	v_mfma_f32_16x16x32_bf16 v[44:47], v[236:239], v[144:147], v[44:47]
	v_mfma_f32_16x16x32_bf16 v[28:31], v[240:243], v[144:147], v[28:31]
	v_mfma_f32_16x16x32_bf16 v[12:15], v[244:247], v[144:147], v[12:15]
	v_mfma_f32_16x16x32_bf16 v[56:59], v[232:235], v[158:161], v[56:59]
	v_mfma_f32_16x16x32_bf16 v[40:43], v[236:239], v[158:161], v[40:43]
	v_mfma_f32_16x16x32_bf16 v[24:27], v[240:243], v[158:161], v[24:27]
	v_mfma_f32_16x16x32_bf16 v[8:11], v[244:247], v[158:161], v[8:11]
	v_mfma_f32_16x16x32_bf16 v[52:55], v[232:235], v[162:165], v[52:55]
	v_mfma_f32_16x16x32_bf16 v[36:39], v[236:239], v[162:165], v[36:39]
	v_mfma_f32_16x16x32_bf16 v[20:23], v[240:243], v[162:165], v[20:23]
	v_mfma_f32_16x16x32_bf16 v[4:7], v[244:247], v[162:165], v[4:7]
	v_mfma_f32_16x16x32_bf16 v[48:51], v[232:235], v[166:169], v[48:51]
	v_mfma_f32_16x16x32_bf16 v[32:35], v[236:239], v[166:169], v[32:35]
	v_mfma_f32_16x16x32_bf16 v[16:19], v[240:243], v[166:169], v[16:19]
	v_mfma_f32_16x16x32_bf16 v[0:3], v[244:247], v[166:169], v[0:3]
	s_waitcnt vmcnt(8)
	s_barrier
	v_add_u32_e32 v128, 0x8000, v141
	v_or_b32_e32 v143, 0x8000, v142
	ds_read_b128 v[130:133], v143
	ds_read_b128 v[134:137], v143 offset:1024
	ds_read_b128 v[144:147], v143 offset:2048
	ds_read_b128 v[158:161], v143 offset:3072
	ds_read_b128 v[162:165], v128
	ds_read_b128 v[166:169], v128 offset:1024
	ds_read_b128 v[174:177], v128 offset:2048
	ds_read_b128 v[178:181], v128 offset:3072
	v_or_b32_e32 v143, 0x10000, v142
	s_waitcnt lgkmcnt(0)
	s_ashr_i32 s13, s12, 31
	v_mfma_f32_16x16x32_bf16 v[124:127], v[162:165], v[130:133], v[124:127]
	s_lshl_b64 s[4:5], s[12:13], 2
	s_add_u32 s4, s62, s4
	s_addc_u32 s5, s63, s5
	v_mfma_f32_16x16x32_bf16 v[120:123], v[162:165], v[134:137], v[120:123]
	v_mfma_f32_16x16x32_bf16 v[116:119], v[162:165], v[144:147], v[116:119]
	v_mfma_f32_16x16x32_bf16 v[112:115], v[162:165], v[158:161], v[112:115]
	v_mfma_f32_16x16x32_bf16 v[108:111], v[166:169], v[130:133], v[108:111]
	v_mfma_f32_16x16x32_bf16 v[104:107], v[166:169], v[134:137], v[104:107]
	v_mfma_f32_16x16x32_bf16 v[100:103], v[166:169], v[144:147], v[100:103]
	v_mfma_f32_16x16x32_bf16 v[96:99], v[166:169], v[158:161], v[96:99]
	v_mfma_f32_16x16x32_bf16 v[92:95], v[174:177], v[130:133], v[92:95]
	v_mfma_f32_16x16x32_bf16 v[88:91], v[174:177], v[134:137], v[88:91]
	v_mfma_f32_16x16x32_bf16 v[84:87], v[174:177], v[144:147], v[84:87]
	v_mfma_f32_16x16x32_bf16 v[80:83], v[174:177], v[158:161], v[80:83]
	v_mfma_f32_16x16x32_bf16 v[76:79], v[178:181], v[130:133], v[76:79]
	v_mfma_f32_16x16x32_bf16 v[72:75], v[178:181], v[134:137], v[72:75]
	v_mfma_f32_16x16x32_bf16 v[68:71], v[178:181], v[144:147], v[68:71]
	v_mfma_f32_16x16x32_bf16 v[64:67], v[178:181], v[158:161], v[64:67]
	ds_read_b128 v[162:165], v128 offset:4096
	ds_read_b128 v[166:169], v128 offset:5120
	ds_read_b128 v[174:177], v128 offset:6144
	ds_read_b128 v[178:181], v128 offset:7168
	s_waitcnt lgkmcnt(0)
	s_waitcnt vmcnt(4)
	s_barrier
	v_mfma_f32_16x16x32_bf16 v[60:63], v[162:165], v[130:133], v[60:63]
	v_add_u32_e32 v128, 0x10000, v141
	v_mfma_f32_16x16x32_bf16 v[56:59], v[162:165], v[134:137], v[56:59]
	v_mfma_f32_16x16x32_bf16 v[52:55], v[162:165], v[144:147], v[52:55]
	v_mfma_f32_16x16x32_bf16 v[48:51], v[162:165], v[158:161], v[48:51]
	v_mfma_f32_16x16x32_bf16 v[44:47], v[166:169], v[130:133], v[44:47]
	v_mfma_f32_16x16x32_bf16 v[40:43], v[166:169], v[134:137], v[40:43]
	v_mfma_f32_16x16x32_bf16 v[36:39], v[166:169], v[144:147], v[36:39]
	v_mfma_f32_16x16x32_bf16 v[32:35], v[166:169], v[158:161], v[32:35]
	v_mfma_f32_16x16x32_bf16 v[28:31], v[174:177], v[130:133], v[28:31]
	v_mfma_f32_16x16x32_bf16 v[24:27], v[174:177], v[134:137], v[24:27]
	v_mfma_f32_16x16x32_bf16 v[20:23], v[174:177], v[144:147], v[20:23]
	v_mfma_f32_16x16x32_bf16 v[16:19], v[174:177], v[158:161], v[16:19]
	v_mfma_f32_16x16x32_bf16 v[12:15], v[178:181], v[130:133], v[12:15]
	v_mfma_f32_16x16x32_bf16 v[8:11], v[178:181], v[134:137], v[8:11]
	v_mfma_f32_16x16x32_bf16 v[4:7], v[178:181], v[144:147], v[4:7]
	v_mfma_f32_16x16x32_bf16 v[0:3], v[178:181], v[158:161], v[0:3]
	ds_read_b128 v[130:133], v143
	ds_read_b128 v[134:137], v143 offset:1024
	ds_read_b128 v[144:147], v143 offset:2048
	ds_read_b128 v[158:161], v143 offset:3072
	ds_read_b128 v[162:165], v128
	ds_read_b128 v[166:169], v128 offset:1024
	ds_read_b128 v[174:177], v128 offset:2048
	ds_read_b128 v[178:181], v128 offset:3072
	s_nop 0
	s_waitcnt lgkmcnt(0)
	s_nop 0
	v_mfma_f32_16x16x32_bf16 v[124:127], v[162:165], v[130:133], v[124:127]
	v_mfma_f32_16x16x32_bf16 v[120:123], v[162:165], v[134:137], v[120:123]
	v_mfma_f32_16x16x32_bf16 v[116:119], v[162:165], v[144:147], v[116:119]
	v_mfma_f32_16x16x32_bf16 v[112:115], v[162:165], v[158:161], v[112:115]
	v_mfma_f32_16x16x32_bf16 v[108:111], v[166:169], v[130:133], v[108:111]
	v_mfma_f32_16x16x32_bf16 v[104:107], v[166:169], v[134:137], v[104:107]
	v_mfma_f32_16x16x32_bf16 v[100:103], v[166:169], v[144:147], v[100:103]
	v_mfma_f32_16x16x32_bf16 v[96:99], v[166:169], v[158:161], v[96:99]
	v_mfma_f32_16x16x32_bf16 v[92:95], v[174:177], v[130:133], v[92:95]
	v_mfma_f32_16x16x32_bf16 v[88:91], v[174:177], v[134:137], v[88:91]
	v_mfma_f32_16x16x32_bf16 v[84:87], v[174:177], v[144:147], v[84:87]
	v_mfma_f32_16x16x32_bf16 v[80:83], v[174:177], v[158:161], v[80:83]
	v_mfma_f32_16x16x32_bf16 v[76:79], v[178:181], v[130:133], v[76:79]
	v_mfma_f32_16x16x32_bf16 v[72:75], v[178:181], v[134:137], v[72:75]
	v_mfma_f32_16x16x32_bf16 v[68:71], v[178:181], v[144:147], v[68:71]
	v_mfma_f32_16x16x32_bf16 v[64:67], v[178:181], v[158:161], v[64:67]
	ds_read_b128 v[162:165], v128 offset:4096
	ds_read_b128 v[166:169], v128 offset:5120
	ds_read_b128 v[174:177], v128 offset:6144
	ds_read_b128 v[178:181], v128 offset:7168
	s_waitcnt lgkmcnt(0)
	s_waitcnt vmcnt(0)
	s_barrier
	v_mfma_f32_16x16x32_bf16 v[60:63], v[162:165], v[130:133], v[60:63]
	v_add_u32_e32 v128, 0x18000, v141
	v_or_b32_e32 v141, 0x18000, v142
	v_mfma_f32_16x16x32_bf16 v[56:59], v[162:165], v[134:137], v[56:59]
	v_mfma_f32_16x16x32_bf16 v[52:55], v[162:165], v[144:147], v[52:55]
	v_mfma_f32_16x16x32_bf16 v[48:51], v[162:165], v[158:161], v[48:51]
	v_mfma_f32_16x16x32_bf16 v[44:47], v[166:169], v[130:133], v[44:47]
	v_mfma_f32_16x16x32_bf16 v[40:43], v[166:169], v[134:137], v[40:43]
	v_mfma_f32_16x16x32_bf16 v[36:39], v[166:169], v[144:147], v[36:39]
	v_mfma_f32_16x16x32_bf16 v[32:35], v[166:169], v[158:161], v[32:35]
	v_mfma_f32_16x16x32_bf16 v[28:31], v[174:177], v[130:133], v[28:31]
	v_mfma_f32_16x16x32_bf16 v[24:27], v[174:177], v[134:137], v[24:27]
	v_mfma_f32_16x16x32_bf16 v[20:23], v[174:177], v[144:147], v[20:23]
	v_mfma_f32_16x16x32_bf16 v[16:19], v[174:177], v[158:161], v[16:19]
	v_mfma_f32_16x16x32_bf16 v[12:15], v[178:181], v[130:133], v[12:15]
	v_mfma_f32_16x16x32_bf16 v[8:11], v[178:181], v[134:137], v[8:11]
	v_mfma_f32_16x16x32_bf16 v[4:7], v[178:181], v[144:147], v[4:7]
	v_mfma_f32_16x16x32_bf16 v[0:3], v[178:181], v[158:161], v[0:3]
	ds_read_b128 v[130:133], v141
	ds_read_b128 v[134:137], v141 offset:1024
	ds_read_b128 v[142:145], v141 offset:2048
	ds_read_b128 v[158:161], v141 offset:3072
	ds_read_b128 v[162:165], v128
	ds_read_b128 v[166:169], v128 offset:1024
	ds_read_b128 v[174:177], v128 offset:2048
	ds_read_b128 v[178:181], v128 offset:3072
	s_nop 0
	s_waitcnt lgkmcnt(0)
	s_nop 0
	v_mfma_f32_16x16x32_bf16 v[124:127], v[162:165], v[130:133], v[124:127]
	v_mfma_f32_16x16x32_bf16 v[120:123], v[162:165], v[134:137], v[120:123]
	v_mfma_f32_16x16x32_bf16 v[116:119], v[162:165], v[142:145], v[116:119]
	v_mfma_f32_16x16x32_bf16 v[162:165], v[162:165], v[158:161], v[112:115]
	v_mfma_f32_16x16x32_bf16 v[108:111], v[166:169], v[130:133], v[108:111]
	v_mfma_f32_16x16x32_bf16 v[104:107], v[166:169], v[134:137], v[104:107]
	v_mfma_f32_16x16x32_bf16 v[100:103], v[166:169], v[142:145], v[100:103]
	v_mfma_f32_16x16x32_bf16 v[96:99], v[166:169], v[158:161], v[96:99]
	v_mfma_f32_16x16x32_bf16 v[92:95], v[174:177], v[130:133], v[92:95]
	v_mfma_f32_16x16x32_bf16 v[88:91], v[174:177], v[134:137], v[88:91]
	v_mfma_f32_16x16x32_bf16 v[84:87], v[174:177], v[142:145], v[84:87]
	v_mfma_f32_16x16x32_bf16 v[80:83], v[174:177], v[158:161], v[80:83]
	v_mfma_f32_16x16x32_bf16 v[76:79], v[178:181], v[130:133], v[76:79]
	v_mfma_f32_16x16x32_bf16 v[72:75], v[178:181], v[134:137], v[72:75]
	v_mfma_f32_16x16x32_bf16 v[68:71], v[178:181], v[142:145], v[68:71]
	v_mfma_f32_16x16x32_bf16 v[64:67], v[178:181], v[158:161], v[64:67]
	ds_read_b128 v[112:115], v128 offset:4096
	ds_read_b128 v[166:169], v128 offset:5120
	ds_read_b128 v[174:177], v128 offset:6144
	ds_read_b128 v[178:181], v128 offset:7168
	s_waitcnt lgkmcnt(0)
	s_barrier
	v_mfma_f32_16x16x32_bf16 v[60:63], v[112:115], v[130:133], v[60:63]
	v_mfma_f32_16x16x32_bf16 v[56:59], v[112:115], v[134:137], v[56:59]
	v_mfma_f32_16x16x32_bf16 v[52:55], v[112:115], v[142:145], v[52:55]
	v_mfma_f32_16x16x32_bf16 v[48:51], v[112:115], v[158:161], v[48:51]
	v_lshlrev_b32_e32 v114, 3, v139
	v_lshlrev_b32_e32 v113, 8, v140
	v_and_b32_e32 v114, 8, v114
	v_add3_u32 v113, s38, v113, v114
	v_lshlrev_b32_e32 v114, 4, v139
	v_mfma_f32_16x16x32_bf16 v[44:47], v[166:169], v[130:133], v[44:47]
	v_lshrrev_b32_e32 v112, 5, v138
	v_xor_b32_e32 v115, v112, v140
	v_lshl_add_u32 v115, v115, 4, v113
	v_mfma_f32_16x16x32_bf16 v[28:31], v[174:177], v[130:133], v[28:31]
	v_mfma_f32_16x16x32_bf16 v[12:15], v[178:181], v[130:133], v[12:15]
	global_load_dwordx4 v[130:133], v114, s[4:5]
	s_waitcnt vmcnt(0)
	v_pk_mul_f32 v[126:127], v[126:127], v[132:133]
	v_pk_mul_f32 v[124:125], v[124:125], v[130:131]
	v_pk_mul_f32 v[122:123], v[122:123], v[132:133]
	v_pk_mul_f32 v[120:121], v[120:121], v[130:131]
	v_cvt_pk_bf16_f32 v124, v124, v125
	v_cvt_pk_bf16_f32 v125, v126, v127
	v_cvt_pk_bf16_f32 v120, v120, v121
	v_cvt_pk_bf16_f32 v121, v122, v123
	v_pk_mul_f32 v[118:119], v[118:119], v[132:133]
	v_pk_mul_f32 v[116:117], v[116:117], v[130:131]
	ds_write2st64_b64 v115, v[124:125], v[120:121] offset1:8
	v_cvt_pk_bf16_f32 v116, v116, v117
	v_cvt_pk_bf16_f32 v117, v118, v119
	v_pk_mul_f32 v[118:119], v[164:165], v[132:133]
	v_pk_mul_f32 v[120:121], v[162:163], v[130:131]
	v_mfma_f32_16x16x32_bf16 v[36:39], v[166:169], v[142:145], v[36:39]
	v_cvt_pk_bf16_f32 v120, v120, v121
	v_cvt_pk_bf16_f32 v121, v118, v119
	ds_write2st64_b64 v115, v[116:117], v[120:121] offset0:16 offset1:24
	global_load_dwordx4 v[116:119], v114, s[4:5] offset:64
	v_bitop3_b32 v115, v112, v140, 2 bitop3:0x36
	v_lshl_add_u32 v115, v115, 4, v113
	v_mfma_f32_16x16x32_bf16 v[32:35], v[166:169], v[158:161], v[32:35]
	s_waitcnt vmcnt(0)
	v_pk_mul_f32 v[102:103], v[102:103], v[118:119]
	v_pk_mul_f32 v[100:101], v[100:101], v[116:117]
	v_pk_mul_f32 v[98:99], v[98:99], v[118:119]
	v_pk_mul_f32 v[96:97], v[96:97], v[116:117]
	v_cvt_pk_bf16_f32 v100, v100, v101
	v_cvt_pk_bf16_f32 v101, v102, v103
	v_cvt_pk_bf16_f32 v96, v96, v97
	v_cvt_pk_bf16_f32 v97, v98, v99
	ds_write2st64_b64 v115, v[100:101], v[96:97] offset0:16 offset1:24
	global_load_dwordx4 v[96:99], v114, s[4:5] offset:128
	v_bitop3_b32 v100, v112, v140, 4 bitop3:0x36
	v_lshl_add_u32 v100, v100, 4, v113
	v_mfma_f32_16x16x32_bf16 v[20:23], v[174:177], v[142:145], v[20:23]
	v_mul_f32_e64 v110, v110, v118
	v_mul_f32_e64 v111, v111, v119
	v_pk_mul_f32 v[108:109], v[108:109], v[116:117]
	v_pk_mul_f32 v[106:107], v[106:107], v[118:119]
	v_mfma_f32_16x16x32_bf16 v[16:19], v[174:177], v[158:161], v[16:19]
	v_mul_f32_e64 v104, v104, v116
	v_mul_f32_e64 v105, v105, v117
	v_cvt_pk_bf16_f32 v108, v108, v109
	v_cvt_pk_bf16_f32 v109, v110, v111
	v_mfma_f32_16x16x32_bf16 v[0:3], v[178:181], v[158:161], v[0:3]
	v_cvt_pk_bf16_f32 v104, v104, v105
	v_cvt_pk_bf16_f32 v105, v106, v107
	ds_write2st64_b64 v115, v[108:109], v[104:105] offset1:8
	v_mfma_f32_16x16x32_bf16 v[8:11], v[178:181], v[134:137], v[8:11]
	s_waitcnt vmcnt(0)
	v_pk_mul_f32 v[86:87], v[86:87], v[98:99]
	v_pk_mul_f32 v[84:85], v[84:85], v[96:97]
	v_pk_mul_f32 v[82:83], v[82:83], v[98:99]
	v_pk_mul_f32 v[80:81], v[80:81], v[96:97]
	v_cvt_pk_bf16_f32 v84, v84, v85
	v_cvt_pk_bf16_f32 v85, v86, v87
	v_cvt_pk_bf16_f32 v80, v80, v81
	v_cvt_pk_bf16_f32 v81, v82, v83
	ds_write2st64_b64 v100, v[84:85], v[80:81] offset0:16 offset1:24
	global_load_dwordx4 v[80:83], v114, s[4:5] offset:192
	v_bitop3_b32 v84, v112, v140, 6 bitop3:0x36
	v_lshl_add_u32 v84, v84, 4, v113
	v_mfma_f32_16x16x32_bf16 v[40:43], v[166:169], v[134:137], v[40:43]
	v_mul_f32_e64 v94, v94, v98
	v_mul_f32_e64 v95, v95, v99
	v_pk_mul_f32 v[92:93], v[92:93], v[96:97]
	v_pk_mul_f32 v[90:91], v[90:91], v[98:99]
	v_mfma_f32_16x16x32_bf16 v[24:27], v[174:177], v[134:137], v[24:27]
	v_mul_f32_e64 v88, v88, v96
	v_mul_f32_e64 v89, v89, v97
	v_cvt_pk_bf16_f32 v92, v92, v93
	v_cvt_pk_bf16_f32 v93, v94, v95
	v_mfma_f32_16x16x32_bf16 v[4:7], v[178:181], v[142:145], v[4:7]
	v_cvt_pk_bf16_f32 v88, v88, v89
	v_cvt_pk_bf16_f32 v89, v90, v91
	ds_write2st64_b64 v100, v[92:93], v[88:89] offset1:8
	s_waitcnt vmcnt(0)
	v_pk_mul_f32 v[70:71], v[70:71], v[82:83]
	v_pk_mul_f32 v[68:69], v[68:69], v[80:81]
	v_pk_mul_f32 v[66:67], v[66:67], v[82:83]
	v_pk_mul_f32 v[64:65], v[64:65], v[80:81]
	v_cvt_pk_bf16_f32 v68, v68, v69
	v_cvt_pk_bf16_f32 v69, v70, v71
	v_cvt_pk_bf16_f32 v64, v64, v65
	v_cvt_pk_bf16_f32 v65, v66, v67
	ds_write2st64_b64 v84, v[68:69], v[64:65] offset0:16 offset1:24
	global_load_dwordx4 v[64:67], v114, s[4:5] offset:256
	v_bitop3_b32 v68, v112, v140, 8 bitop3:0x36
	v_lshl_add_u32 v68, v68, 4, v113
	v_pk_mul_f32 v[78:79], v[78:79], v[82:83]
	v_pk_mul_f32 v[76:77], v[76:77], v[80:81]
	v_pk_mul_f32 v[74:75], v[74:75], v[82:83]
	v_pk_mul_f32 v[72:73], v[72:73], v[80:81]
	v_cvt_pk_bf16_f32 v76, v76, v77
	v_cvt_pk_bf16_f32 v77, v78, v79
	v_cvt_pk_bf16_f32 v72, v72, v73
	v_cvt_pk_bf16_f32 v73, v74, v75
	ds_write2st64_b64 v84, v[76:77], v[72:73] offset1:8
	s_waitcnt vmcnt(0)
	v_pk_mul_f32 v[54:55], v[54:55], v[66:67]
	v_pk_mul_f32 v[52:53], v[52:53], v[64:65]
	v_pk_mul_f32 v[50:51], v[50:51], v[66:67]
	v_pk_mul_f32 v[48:49], v[48:49], v[64:65]
	v_cvt_pk_bf16_f32 v52, v52, v53
	v_cvt_pk_bf16_f32 v53, v54, v55
	v_cvt_pk_bf16_f32 v48, v48, v49
	v_cvt_pk_bf16_f32 v49, v50, v51
	ds_write2st64_b64 v68, v[52:53], v[48:49] offset0:16 offset1:24
	global_load_dwordx4 v[48:51], v114, s[4:5] offset:320
	v_bitop3_b32 v52, v112, v140, 10 bitop3:0x36
	v_lshl_add_u32 v52, v52, 4, v113
	v_pk_mul_f32 v[62:63], v[62:63], v[66:67]
	v_pk_mul_f32 v[60:61], v[60:61], v[64:65]
	v_pk_mul_f32 v[58:59], v[58:59], v[66:67]
	v_pk_mul_f32 v[56:57], v[56:57], v[64:65]
	v_cvt_pk_bf16_f32 v60, v60, v61
	v_cvt_pk_bf16_f32 v61, v62, v63
	v_cvt_pk_bf16_f32 v56, v56, v57
	v_cvt_pk_bf16_f32 v57, v58, v59
	ds_write2st64_b64 v68, v[60:61], v[56:57] offset1:8
	s_waitcnt vmcnt(0)
	v_pk_mul_f32 v[38:39], v[38:39], v[50:51]
	v_pk_mul_f32 v[36:37], v[36:37], v[48:49]
	v_pk_mul_f32 v[34:35], v[34:35], v[50:51]
	v_pk_mul_f32 v[32:33], v[32:33], v[48:49]
	v_cvt_pk_bf16_f32 v36, v36, v37
	v_cvt_pk_bf16_f32 v37, v38, v39
	v_cvt_pk_bf16_f32 v32, v32, v33
	v_cvt_pk_bf16_f32 v33, v34, v35
	ds_write2st64_b64 v52, v[36:37], v[32:33] offset0:16 offset1:24
	global_load_dwordx4 v[32:35], v114, s[4:5] offset:384
	v_bitop3_b32 v36, v112, v140, 12 bitop3:0x36
	v_lshl_add_u32 v36, v36, 4, v113
	v_pk_mul_f32 v[46:47], v[46:47], v[50:51]
	v_pk_mul_f32 v[44:45], v[44:45], v[48:49]
	v_pk_mul_f32 v[42:43], v[42:43], v[50:51]
	v_pk_mul_f32 v[40:41], v[40:41], v[48:49]
	v_cvt_pk_bf16_f32 v44, v44, v45
	v_cvt_pk_bf16_f32 v45, v46, v47
	v_cvt_pk_bf16_f32 v40, v40, v41
	v_cvt_pk_bf16_f32 v41, v42, v43
	ds_write2st64_b64 v52, v[44:45], v[40:41] offset1:8
	s_waitcnt vmcnt(0)
	v_pk_mul_f32 v[22:23], v[22:23], v[34:35]
	v_pk_mul_f32 v[20:21], v[20:21], v[32:33]
	v_pk_mul_f32 v[18:19], v[18:19], v[34:35]
	v_pk_mul_f32 v[16:17], v[16:17], v[32:33]
	v_cvt_pk_bf16_f32 v20, v20, v21
	v_cvt_pk_bf16_f32 v21, v22, v23
	v_cvt_pk_bf16_f32 v16, v16, v17
	v_cvt_pk_bf16_f32 v17, v18, v19
	ds_write2st64_b64 v36, v[20:21], v[16:17] offset0:16 offset1:24
	global_load_dwordx4 v[16:19], v114, s[4:5] offset:448
	s_lshr_b32 s4, s40, 6
	s_and_b32 s5, s39, -16
	s_or_b32 s4, s4, s5
	v_bitop3_b32 v20, v112, v140, 14 bitop3:0x36
	s_ashr_i32 s5, s4, 31
	v_pk_mul_f32 v[30:31], v[30:31], v[34:35]
	v_pk_mul_f32 v[28:29], v[28:29], v[32:33]
	v_pk_mul_f32 v[26:27], v[26:27], v[34:35]
	v_pk_mul_f32 v[24:25], v[24:25], v[32:33]
	v_lshl_add_u32 v20, v20, 4, v113
	s_lshl_b64 s[4:5], s[4:5], 19
	v_cvt_pk_bf16_f32 v28, v28, v29
	v_cvt_pk_bf16_f32 v29, v30, v31
	v_cvt_pk_bf16_f32 v24, v24, v25
	v_cvt_pk_bf16_f32 v25, v26, v27
	s_add_u32 s4, s26, s4
	ds_write2st64_b64 v36, v[28:29], v[24:25] offset1:8
	s_addc_u32 s5, s27, s5
	s_and_b32 s8, s12, 0xf80
	s_lshl_b32 s8, s8, 1
	s_add_u32 s4, s4, s8
	s_addc_u32 s5, s5, 0
	s_waitcnt vmcnt(0)
	v_pk_mul_f32 v[2:3], v[2:3], v[18:19]
	v_pk_mul_f32 v[0:1], v[0:1], v[16:17]
	v_pk_mul_f32 v[14:15], v[14:15], v[18:19]
	v_pk_mul_f32 v[12:13], v[12:13], v[16:17]
	v_pk_mul_f32 v[10:11], v[10:11], v[18:19]
	v_pk_mul_f32 v[8:9], v[8:9], v[16:17]
	v_cvt_pk_bf16_f32 v0, v0, v1
	v_cvt_pk_bf16_f32 v1, v2, v3
	v_xor_b32_e32 v3, v139, v138
	v_cvt_pk_bf16_f32 v12, v12, v13
	v_cvt_pk_bf16_f32 v13, v14, v15
	v_cvt_pk_bf16_f32 v8, v8, v9
	v_cvt_pk_bf16_f32 v9, v10, v11
	v_lshlrev_b32_e32 v3, 4, v3
	ds_write2st64_b64 v20, v[12:13], v[8:9] offset1:8
	v_pk_mul_f32 v[6:7], v[6:7], v[18:19]
	v_pk_mul_f32 v[4:5], v[4:5], v[16:17]
	v_lshlrev_b32_e32 v2, 8, v139
	v_and_b32_e32 v8, 0xf0, v3
	v_cvt_pk_bf16_f32 v4, v4, v5
	v_cvt_pk_bf16_f32 v5, v6, v7
	v_add3_u32 v2, s38, v2, v8
	ds_write2st64_b64 v20, v[4:5], v[0:1] offset0:16 offset1:24
	ds_read_b128 v[2:5], v2
	v_lshlrev_b32_e32 v0, 4, v138
	v_and_b32_e32 v128, 0xf0, v0
	v_lshl_add_u64 v[0:1], s[4:5], 0, v[128:129]
	v_lshlrev_b32_e32 v128, 13, v139
	v_lshl_add_u64 v[6:7], v[0:1], 0, v[128:129]
	s_waitcnt lgkmcnt(0)
	global_store_dwordx4 v[6:7], v[2:5], off
	v_or_b32_e32 v6, 4, v139
	v_lshlrev_b32_e32 v128, 13, v6
	v_bitop3_b32 v3, v139, v138, 4 bitop3:0x36
	v_lshlrev_b32_e32 v3, 4, v3
	v_lshlrev_b32_e32 v2, 8, v6
	v_and_b32_e32 v3, 0xf0, v3
	v_add3_u32 v2, s38, v2, v3
	ds_read_b128 v[2:5], v2
	v_lshl_add_u64 v[6:7], v[0:1], 0, v[128:129]
	s_waitcnt lgkmcnt(0)
	global_store_dwordx4 v[6:7], v[2:5], off
	s_nop 1
	v_bitop3_b32 v3, v139, v138, 8 bitop3:0x36
	v_or_b32_e32 v6, 8, v139
	v_lshlrev_b32_e32 v3, 4, v3
	v_lshlrev_b32_e32 v2, 8, v6
	v_and_b32_e32 v3, 0xf0, v3
	v_add3_u32 v2, s38, v2, v3
	ds_read_b128 v[2:5], v2
	v_lshlrev_b32_e32 v128, 13, v6
	v_lshl_add_u64 v[6:7], v[0:1], 0, v[128:129]
	s_waitcnt lgkmcnt(0)
	global_store_dwordx4 v[6:7], v[2:5], off
	s_nop 1
	v_bitop3_b32 v3, v139, v138, 12 bitop3:0x36
	v_or_b32_e32 v6, 12, v139
	v_lshlrev_b32_e32 v3, 4, v3
	v_lshlrev_b32_e32 v2, 8, v6
	v_and_b32_e32 v3, 0xf0, v3
	v_add3_u32 v2, s38, v2, v3
	ds_read_b128 v[2:5], v2
	v_lshlrev_b32_e32 v128, 13, v6
	v_lshl_add_u64 v[6:7], v[0:1], 0, v[128:129]
	s_waitcnt lgkmcnt(0)
	global_store_dwordx4 v[6:7], v[2:5], off
	v_or_b32_e32 v6, 16, v139
	s_nop 0
	v_lshlrev_b32_e32 v2, 8, v6
	v_add3_u32 v2, s38, v2, v8
	ds_read_b128 v[2:5], v2
	v_lshlrev_b32_e32 v128, 13, v6
	v_lshl_add_u64 v[6:7], v[0:1], 0, v[128:129]
	s_waitcnt lgkmcnt(0)
	global_store_dwordx4 v[6:7], v[2:5], off
	s_nop 1
	v_bitop3_b32 v3, v139, v138, 20 bitop3:0x36
	v_or_b32_e32 v6, 20, v139
	v_lshlrev_b32_e32 v3, 4, v3
	v_lshlrev_b32_e32 v2, 8, v6
	v_and_b32_e32 v3, 0xf0, v3
	v_add3_u32 v2, s38, v2, v3
	ds_read_b128 v[2:5], v2
	v_lshlrev_b32_e32 v128, 13, v6
	v_lshl_add_u64 v[6:7], v[0:1], 0, v[128:129]
	s_waitcnt lgkmcnt(0)
	global_store_dwordx4 v[6:7], v[2:5], off
	s_nop 1
	v_bitop3_b32 v3, v139, v138, 24 bitop3:0x36
	v_or_b32_e32 v6, 24, v139
	v_lshlrev_b32_e32 v3, 4, v3
	v_lshlrev_b32_e32 v2, 8, v6
	v_and_b32_e32 v3, 0xf0, v3
	v_add3_u32 v2, s38, v2, v3
	ds_read_b128 v[2:5], v2
	v_lshlrev_b32_e32 v128, 13, v6
	v_lshl_add_u64 v[6:7], v[0:1], 0, v[128:129]
	s_waitcnt lgkmcnt(0)
	global_store_dwordx4 v[6:7], v[2:5], off
	s_nop 1
	v_bitop3_b32 v3, v139, v138, 28 bitop3:0x36
	v_or_b32_e32 v6, 28, v139
	v_lshlrev_b32_e32 v3, 4, v3
	v_lshlrev_b32_e32 v2, 8, v6
	v_and_b32_e32 v3, 0xf0, v3
	v_add3_u32 v2, s38, v2, v3
	ds_read_b128 v[2:5], v2
	v_lshlrev_b32_e32 v128, 13, v6
	v_lshl_add_u64 v[6:7], v[0:1], 0, v[128:129]
	s_waitcnt lgkmcnt(0)
	global_store_dwordx4 v[6:7], v[2:5], off
	v_or_b32_e32 v6, 32, v139
	s_nop 0
	v_lshlrev_b32_e32 v2, 8, v6
	v_add3_u32 v2, s38, v2, v8
	ds_read_b128 v[2:5], v2
	v_lshlrev_b32_e32 v128, 13, v6
	v_lshl_add_u64 v[6:7], v[0:1], 0, v[128:129]
	s_waitcnt lgkmcnt(0)
	global_store_dwordx4 v[6:7], v[2:5], off
	s_nop 1
	v_bitop3_b32 v3, v139, v138, 36 bitop3:0x36
	v_or_b32_e32 v6, 36, v139
	v_lshlrev_b32_e32 v3, 4, v3
	v_lshlrev_b32_e32 v2, 8, v6
	v_and_b32_e32 v3, 0xf0, v3
	v_add3_u32 v2, s38, v2, v3
	ds_read_b128 v[2:5], v2
	v_lshlrev_b32_e32 v128, 13, v6
	v_lshl_add_u64 v[6:7], v[0:1], 0, v[128:129]
	s_waitcnt lgkmcnt(0)
	global_store_dwordx4 v[6:7], v[2:5], off
	s_nop 1
	v_bitop3_b32 v3, v139, v138, 40 bitop3:0x36
	v_or_b32_e32 v6, 40, v139
	v_lshlrev_b32_e32 v3, 4, v3
	v_lshlrev_b32_e32 v2, 8, v6
	v_and_b32_e32 v3, 0xf0, v3
	v_add3_u32 v2, s38, v2, v3
	ds_read_b128 v[2:5], v2
	v_lshlrev_b32_e32 v128, 13, v6
	v_lshl_add_u64 v[6:7], v[0:1], 0, v[128:129]
	s_waitcnt lgkmcnt(0)
	global_store_dwordx4 v[6:7], v[2:5], off
	s_nop 1
	v_bitop3_b32 v3, v139, v138, 44 bitop3:0x36
	v_or_b32_e32 v6, 44, v139
	v_lshlrev_b32_e32 v3, 4, v3
	v_lshlrev_b32_e32 v2, 8, v6
	v_and_b32_e32 v3, 0xf0, v3
	v_add3_u32 v2, s38, v2, v3
	ds_read_b128 v[2:5], v2
	v_lshlrev_b32_e32 v128, 13, v6
	v_lshl_add_u64 v[6:7], v[0:1], 0, v[128:129]
	s_waitcnt lgkmcnt(0)
	global_store_dwordx4 v[6:7], v[2:5], off
	v_or_b32_e32 v6, 48, v139
	s_nop 0
	v_lshlrev_b32_e32 v2, 8, v6
	v_add3_u32 v2, s38, v2, v8
	ds_read_b128 v[2:5], v2
	v_lshlrev_b32_e32 v128, 13, v6
	v_lshl_add_u64 v[6:7], v[0:1], 0, v[128:129]
	s_waitcnt lgkmcnt(0)
	global_store_dwordx4 v[6:7], v[2:5], off
	s_nop 1
	v_bitop3_b32 v3, v139, v138, 52 bitop3:0x36
	v_or_b32_e32 v6, 52, v139
	v_lshlrev_b32_e32 v3, 4, v3
	v_lshlrev_b32_e32 v2, 8, v6
	v_and_b32_e32 v3, 0xf0, v3
	v_add3_u32 v2, s38, v2, v3
	ds_read_b128 v[2:5], v2
	v_lshlrev_b32_e32 v128, 13, v6
	v_lshl_add_u64 v[6:7], v[0:1], 0, v[128:129]
	s_waitcnt lgkmcnt(0)
	global_store_dwordx4 v[6:7], v[2:5], off
	s_nop 1
	v_bitop3_b32 v3, v139, v138, 56 bitop3:0x36
	v_or_b32_e32 v6, 56, v139
	v_lshlrev_b32_e32 v3, 4, v3
	v_lshlrev_b32_e32 v2, 8, v6
	v_and_b32_e32 v3, 0xf0, v3
	v_add3_u32 v2, s38, v2, v3
	ds_read_b128 v[2:5], v2
	v_lshlrev_b32_e32 v128, 13, v6
	v_lshl_add_u64 v[6:7], v[0:1], 0, v[128:129]
	s_waitcnt lgkmcnt(0)
	global_store_dwordx4 v[6:7], v[2:5], off
	s_nop 1
	v_bitop3_b32 v4, v139, v138, 60 bitop3:0x36
	v_or_b32_e32 v3, 60, v139
	v_lshlrev_b32_e32 v4, 4, v4
	v_lshlrev_b32_e32 v2, 8, v3
	v_and_b32_e32 v4, 0xf0, v4
	v_add3_u32 v2, s38, v2, v4
	v_lshlrev_b32_e32 v128, 12, v3
	s_branch .LBB0_803

.Lgsk4_loop:
	s_add_i32 s9, s8, 0xfffe8000
	s_and_b32 s10, s8, 0x18000
	s_waitcnt vmcnt(8) lgkmcnt(0)
	s_barrier
	s_and_b32 s9, s9, 0x18000
	s_add_i32 s10, s7, s10
	v_add_u32_e32 v128, s9, v139
	v_or_b32_e32 v141, s9, v140
	s_add_i32 s15, s10, 0x400
	s_add_i32 s11, s10, 0x800
	s_add_i32 s9, s10, 0xc00
	s_add_i32 s8, s8, 0x8000
	s_cmp_eq_u32 s8, 0x100000
	ds_read_b128 v[174:177], v128
	ds_read_b128 v[178:181], v128 offset:1024
	ds_read_b128 v[182:185], v128 offset:2048
	ds_read_b128 v[186:189], v128 offset:3072
	v_mfma_f32_16x16x32_bf16 v[60:63], v[142:145], v[232:235], v[60:63]
	v_mfma_f32_16x16x32_bf16 v[44:47], v[142:145], v[236:239], v[44:47]
	v_mfma_f32_16x16x32_bf16 v[28:31], v[142:145], v[240:243], v[28:31]
	v_mfma_f32_16x16x32_bf16 v[12:15], v[142:145], v[244:247], v[12:15]
	v_mfma_f32_16x16x32_bf16 v[56:59], v[158:161], v[232:235], v[56:59]
	ds_read_b128 v[142:145], v141
	v_mfma_f32_16x16x32_bf16 v[40:43], v[158:161], v[236:239], v[40:43]
	v_mfma_f32_16x16x32_bf16 v[24:27], v[158:161], v[240:243], v[24:27]
	v_mfma_f32_16x16x32_bf16 v[8:11], v[158:161], v[244:247], v[8:11]
	v_mfma_f32_16x16x32_bf16 v[52:55], v[162:165], v[232:235], v[52:55]
	ds_read_b128 v[158:161], v141 offset:1024
	v_mfma_f32_16x16x32_bf16 v[36:39], v[162:165], v[236:239], v[36:39]
	v_mfma_f32_16x16x32_bf16 v[20:23], v[162:165], v[240:243], v[20:23]
	v_mfma_f32_16x16x32_bf16 v[4:7], v[162:165], v[244:247], v[4:7]
	v_mfma_f32_16x16x32_bf16 v[48:51], v[166:169], v[232:235], v[48:51]
	ds_read_b128 v[162:165], v141 offset:2048
	v_mfma_f32_16x16x32_bf16 v[32:35], v[166:169], v[236:239], v[32:35]
	v_mfma_f32_16x16x32_bf16 v[16:19], v[166:169], v[240:243], v[16:19]
	v_mfma_f32_16x16x32_bf16 v[0:3], v[166:169], v[244:247], v[0:3]
	s_waitcnt lgkmcnt(2)
	v_mfma_f32_16x16x32_bf16 v[124:127], v[142:145], v[174:177], v[124:127]
	ds_read_b128 v[166:169], v141 offset:3072
	v_mfma_f32_16x16x32_bf16 v[108:111], v[142:145], v[178:181], v[108:111]
	ds_read_b128 v[232:235], v128 offset:4096
	ds_read_b128 v[236:239], v128 offset:5120
	v_mfma_f32_16x16x32_bf16 v[92:95], v[142:145], v[182:185], v[92:95]
	ds_read_b128 v[240:243], v128 offset:6144
	ds_read_b128 v[244:247], v128 offset:7168
	s_mov_b32 m0, s10
	v_mfma_f32_16x16x32_bf16 v[76:79], v[142:145], v[186:189], v[76:79]
	global_load_lds_dwordx4 v[136:137], off
	v_lshl_add_u64 v[136:137], v[136:137], 0, 64
	s_waitcnt lgkmcnt(6)
	v_mfma_f32_16x16x32_bf16 v[120:123], v[158:161], v[174:177], v[120:123]
	v_mfma_f32_16x16x32_bf16 v[104:107], v[158:161], v[178:181], v[104:107]
	v_mfma_f32_16x16x32_bf16 v[88:91], v[158:161], v[182:185], v[88:91]
	s_mov_b32 m0, s15
	v_mfma_f32_16x16x32_bf16 v[72:75], v[158:161], v[186:189], v[72:75]
	global_load_lds_dwordx4 v[134:135], off
	v_lshl_add_u64 v[134:135], v[134:135], 0, 64
	s_waitcnt lgkmcnt(5)
	v_mfma_f32_16x16x32_bf16 v[116:119], v[162:165], v[174:177], v[116:119]
	v_mfma_f32_16x16x32_bf16 v[100:103], v[162:165], v[178:181], v[100:103]
	v_mfma_f32_16x16x32_bf16 v[84:87], v[162:165], v[182:185], v[84:87]
	s_mov_b32 m0, s11
	v_mfma_f32_16x16x32_bf16 v[68:71], v[162:165], v[186:189], v[68:71]
	global_load_lds_dwordx4 v[132:133], off
	v_lshl_add_u64 v[132:133], v[132:133], 0, 64
	s_waitcnt lgkmcnt(4)
	v_mfma_f32_16x16x32_bf16 v[112:115], v[166:169], v[174:177], v[112:115]
	v_mfma_f32_16x16x32_bf16 v[96:99], v[166:169], v[178:181], v[96:99]
	v_mfma_f32_16x16x32_bf16 v[80:83], v[166:169], v[182:185], v[80:83]
	s_mov_b32 m0, s9
	v_mfma_f32_16x16x32_bf16 v[64:67], v[166:169], v[186:189], v[64:67]
	global_load_lds_dwordx4 v[130:131], off
	v_lshl_add_u64 v[130:131], v[130:131], 0, 64
	s_cbranch_scc0 .Lgsk4_loop
	s_waitcnt lgkmcnt(0)
	v_mfma_f32_16x16x32_bf16 v[60:63], v[142:145], v[232:235], v[60:63]
	v_mfma_f32_16x16x32_bf16 v[44:47], v[142:145], v[236:239], v[44:47]
	v_mfma_f32_16x16x32_bf16 v[28:31], v[142:145], v[240:243], v[28:31]
	v_mfma_f32_16x16x32_bf16 v[12:15], v[142:145], v[244:247], v[12:15]
	v_mfma_f32_16x16x32_bf16 v[56:59], v[158:161], v[232:235], v[56:59]
	v_mfma_f32_16x16x32_bf16 v[40:43], v[158:161], v[236:239], v[40:43]
	v_mfma_f32_16x16x32_bf16 v[24:27], v[158:161], v[240:243], v[24:27]
	v_mfma_f32_16x16x32_bf16 v[8:11], v[158:161], v[244:247], v[8:11]
	v_mfma_f32_16x16x32_bf16 v[52:55], v[162:165], v[232:235], v[52:55]
	v_mfma_f32_16x16x32_bf16 v[36:39], v[162:165], v[236:239], v[36:39]
	v_mfma_f32_16x16x32_bf16 v[20:23], v[162:165], v[240:243], v[20:23]
	v_mfma_f32_16x16x32_bf16 v[4:7], v[162:165], v[244:247], v[4:7]
	v_mfma_f32_16x16x32_bf16 v[48:51], v[166:169], v[232:235], v[48:51]
	v_mfma_f32_16x16x32_bf16 v[32:35], v[166:169], v[236:239], v[32:35]
	v_mfma_f32_16x16x32_bf16 v[16:19], v[166:169], v[240:243], v[16:19]
	v_mfma_f32_16x16x32_bf16 v[0:3], v[166:169], v[244:247], v[0:3]
	s_waitcnt vmcnt(8)
	s_barrier
	v_add_u32_e32 v128, 0x8000, v139
	v_or_b32_e32 v141, 0x8000, v140
	ds_read_b128 v[130:133], v141
	ds_read_b128 v[134:137], v141 offset:1024
	ds_read_b128 v[142:145], v141 offset:2048
	ds_read_b128 v[158:161], v141 offset:3072
	ds_read_b128 v[162:165], v128
	ds_read_b128 v[166:169], v128 offset:1024
	ds_read_b128 v[174:177], v128 offset:2048
	ds_read_b128 v[178:181], v128 offset:3072
	s_lshl_b32 s8, s6, 8
	s_waitcnt lgkmcnt(0)
	s_and_b32 s15, s8, 0xffffc000
	v_mfma_f32_16x16x32_bf16 v[124:127], v[130:133], v[162:165], v[124:127]
	s_ashr_i32 s7, s6, 1
	s_and_b32 s7, s7, 0xffffff80
	s_and_b32 s6, s6, 0xc0
	v_mfma_f32_16x16x32_bf16 v[120:123], v[134:137], v[162:165], v[120:123]
	s_add_i32 s8, s4, s7
	s_or_b32 s4, s5, s6
	s_ashr_i32 s10, s4, 6
	v_mfma_f32_16x16x32_bf16 v[182:185], v[142:145], v[162:165], v[116:119]
	s_ashr_i32 s11, s10, 31
	v_mfma_f32_16x16x32_bf16 v[112:115], v[158:161], v[162:165], v[112:115]
	v_mfma_f32_16x16x32_bf16 v[108:111], v[130:133], v[166:169], v[108:111]
	v_mfma_f32_16x16x32_bf16 v[104:107], v[134:137], v[166:169], v[104:107]
	v_mfma_f32_16x16x32_bf16 v[100:103], v[142:145], v[166:169], v[100:103]
	v_mfma_f32_16x16x32_bf16 v[96:99], v[158:161], v[166:169], v[96:99]
	v_mfma_f32_16x16x32_bf16 v[92:95], v[130:133], v[174:177], v[92:95]
	v_mfma_f32_16x16x32_bf16 v[88:91], v[134:137], v[174:177], v[88:91]
	v_mfma_f32_16x16x32_bf16 v[84:87], v[142:145], v[174:177], v[84:87]
	v_mfma_f32_16x16x32_bf16 v[80:83], v[158:161], v[174:177], v[80:83]
	ds_read_b128 v[116:119], v128 offset:4096
	ds_read_b128 v[162:165], v128 offset:5120
	ds_read_b128 v[166:169], v128 offset:6144
	ds_read_b128 v[174:177], v128 offset:7168
	s_waitcnt lgkmcnt(0)
	s_waitcnt vmcnt(4)
	s_barrier
	v_mfma_f32_16x16x32_bf16 v[76:79], v[130:133], v[178:181], v[76:79]
	v_mfma_f32_16x16x32_bf16 v[72:75], v[134:137], v[178:181], v[72:75]
	v_mfma_f32_16x16x32_bf16 v[68:71], v[142:145], v[178:181], v[68:71]
	v_mfma_f32_16x16x32_bf16 v[64:67], v[158:161], v[178:181], v[64:67]
	v_mfma_f32_16x16x32_bf16 v[60:63], v[130:133], v[116:119], v[60:63]
	v_mfma_f32_16x16x32_bf16 v[56:59], v[134:137], v[116:119], v[56:59]
	v_mfma_f32_16x16x32_bf16 v[52:55], v[142:145], v[116:119], v[52:55]
	v_mfma_f32_16x16x32_bf16 v[48:51], v[158:161], v[116:119], v[48:51]
	v_add_u32_e32 v117, 0x10000, v139
	v_or_b32_e32 v119, 0x10000, v140
	v_and_b32_e32 v116, 15, v138
	v_mfma_f32_16x16x32_bf16 v[44:47], v[130:133], v[162:165], v[44:47]
	v_and_b32_e32 v118, 63, v138
	v_mfma_f32_16x16x32_bf16 v[40:43], v[134:137], v[162:165], v[40:43]
	v_mfma_f32_16x16x32_bf16 v[36:39], v[142:145], v[162:165], v[36:39]
	v_mfma_f32_16x16x32_bf16 v[32:35], v[158:161], v[162:165], v[32:35]
	v_mfma_f32_16x16x32_bf16 v[28:31], v[130:133], v[166:169], v[28:31]
	v_mfma_f32_16x16x32_bf16 v[24:27], v[134:137], v[166:169], v[24:27]
	v_mfma_f32_16x16x32_bf16 v[20:23], v[142:145], v[166:169], v[20:23]
	v_mfma_f32_16x16x32_bf16 v[16:19], v[158:161], v[166:169], v[16:19]
	v_mfma_f32_16x16x32_bf16 v[12:15], v[130:133], v[174:177], v[12:15]
	v_mfma_f32_16x16x32_bf16 v[8:11], v[134:137], v[174:177], v[8:11]
	v_mfma_f32_16x16x32_bf16 v[4:7], v[142:145], v[174:177], v[4:7]
	v_mfma_f32_16x16x32_bf16 v[0:3], v[158:161], v[174:177], v[0:3]
	ds_read_b128 v[130:133], v119
	ds_read_b128 v[134:137], v119 offset:1024
	ds_read_b128 v[142:145], v119 offset:2048
	ds_read_b128 v[158:161], v119 offset:3072
	ds_read_b128 v[162:165], v117
	ds_read_b128 v[166:169], v117 offset:1024
	ds_read_b128 v[174:177], v117 offset:2048
	ds_read_b128 v[178:181], v117 offset:3072
	v_or_b32_e32 v119, 0x18000, v140
	s_waitcnt lgkmcnt(0)
	s_nop 0
	v_mfma_f32_16x16x32_bf16 v[124:127], v[130:133], v[162:165], v[124:127]
	v_mfma_f32_16x16x32_bf16 v[120:123], v[134:137], v[162:165], v[120:123]
	v_mfma_f32_16x16x32_bf16 v[182:185], v[142:145], v[162:165], v[182:185]
	v_mfma_f32_16x16x32_bf16 v[112:115], v[158:161], v[162:165], v[112:115]
	v_mfma_f32_16x16x32_bf16 v[108:111], v[130:133], v[166:169], v[108:111]
	v_mfma_f32_16x16x32_bf16 v[104:107], v[134:137], v[166:169], v[104:107]
	v_mfma_f32_16x16x32_bf16 v[100:103], v[142:145], v[166:169], v[100:103]
	v_mfma_f32_16x16x32_bf16 v[162:165], v[158:161], v[166:169], v[96:99]
	v_mfma_f32_16x16x32_bf16 v[92:95], v[130:133], v[174:177], v[92:95]
	v_mfma_f32_16x16x32_bf16 v[88:91], v[134:137], v[174:177], v[88:91]
	v_mfma_f32_16x16x32_bf16 v[84:87], v[142:145], v[174:177], v[84:87]
	v_mfma_f32_16x16x32_bf16 v[80:83], v[158:161], v[174:177], v[80:83]
	v_mfma_f32_16x16x32_bf16 v[76:79], v[130:133], v[178:181], v[76:79]
	v_mfma_f32_16x16x32_bf16 v[72:75], v[134:137], v[178:181], v[72:75]
	v_mfma_f32_16x16x32_bf16 v[68:71], v[142:145], v[178:181], v[68:71]
	v_mfma_f32_16x16x32_bf16 v[64:67], v[158:161], v[178:181], v[64:67]
	ds_read_b128 v[96:99], v117 offset:4096
	ds_read_b128 v[166:169], v117 offset:5120
	ds_read_b128 v[174:177], v117 offset:6144
	ds_read_b128 v[178:181], v117 offset:7168
	s_waitcnt lgkmcnt(0)
	s_waitcnt vmcnt(0)
	s_barrier
	v_mfma_f32_16x16x32_bf16 v[60:63], v[130:133], v[96:99], v[60:63]
	v_add_u32_e32 v117, 0x18000, v139
	v_mfma_f32_16x16x32_bf16 v[56:59], v[134:137], v[96:99], v[56:59]
	v_mfma_f32_16x16x32_bf16 v[52:55], v[142:145], v[96:99], v[52:55]
	v_mfma_f32_16x16x32_bf16 v[48:51], v[158:161], v[96:99], v[48:51]
	v_mfma_f32_16x16x32_bf16 v[44:47], v[130:133], v[166:169], v[44:47]
	v_mfma_f32_16x16x32_bf16 v[40:43], v[134:137], v[166:169], v[40:43]
	v_mfma_f32_16x16x32_bf16 v[36:39], v[142:145], v[166:169], v[36:39]
	v_mfma_f32_16x16x32_bf16 v[32:35], v[158:161], v[166:169], v[32:35]
	v_mfma_f32_16x16x32_bf16 v[28:31], v[130:133], v[174:177], v[28:31]
	v_mfma_f32_16x16x32_bf16 v[24:27], v[134:137], v[174:177], v[24:27]
	v_mfma_f32_16x16x32_bf16 v[20:23], v[142:145], v[174:177], v[20:23]
	v_mfma_f32_16x16x32_bf16 v[16:19], v[158:161], v[174:177], v[16:19]
	v_mfma_f32_16x16x32_bf16 v[12:15], v[130:133], v[178:181], v[12:15]
	v_mfma_f32_16x16x32_bf16 v[8:11], v[134:137], v[178:181], v[8:11]
	v_mfma_f32_16x16x32_bf16 v[4:7], v[142:145], v[178:181], v[4:7]
	v_mfma_f32_16x16x32_bf16 v[0:3], v[158:161], v[178:181], v[0:3]
	ds_read_b128 v[130:133], v119
	ds_read_b128 v[134:137], v119 offset:1024
	ds_read_b128 v[140:143], v119 offset:2048
	ds_read_b128 v[144:147], v119 offset:3072
	ds_read_b128 v[96:99], v117
	ds_read_b128 v[158:161], v117 offset:1024
	ds_read_b128 v[166:169], v117 offset:2048
	ds_read_b128 v[174:177], v117 offset:3072
	v_and_b32_e32 v119, 7, v138
	s_waitcnt lgkmcnt(0)
	s_nop 0
	v_mfma_f32_16x16x32_bf16 v[124:127], v[130:133], v[96:99], v[124:127]
	v_mfma_f32_16x16x32_bf16 v[178:181], v[134:137], v[96:99], v[120:123]
	v_mfma_f32_16x16x32_bf16 v[182:185], v[140:143], v[96:99], v[182:185]
	s_nop 5
	v_mul_f32_e32 v128, v125, v125
	v_fmac_f32_e32 v128, v124, v124
	v_fmac_f32_e32 v128, v126, v126
	v_mfma_f32_16x16x32_bf16 v[112:115], v[144:147], v[96:99], v[112:115]
	v_cvt_pk_bf16_f32 v124, v124, v125
	v_cvt_pk_bf16_f32 v125, v126, v127
	v_fmac_f32_e32 v128, v127, v127
	v_mfma_f32_16x16x32_bf16 v[108:111], v[130:133], v[158:161], v[108:111]
	v_cvt_pk_bf16_f32 v127, v180, v181
	v_mfma_f32_16x16x32_bf16 v[104:107], v[134:137], v[158:161], v[104:107]
	v_mfma_f32_16x16x32_bf16 v[96:99], v[140:143], v[158:161], v[100:103]
	v_mfma_f32_16x16x32_bf16 v[100:103], v[144:147], v[158:161], v[162:165]
	v_mfma_f32_16x16x32_bf16 v[92:95], v[130:133], v[166:169], v[92:95]
	v_mfma_f32_16x16x32_bf16 v[88:91], v[134:137], v[166:169], v[88:91]
	v_mfma_f32_16x16x32_bf16 v[84:87], v[140:143], v[166:169], v[84:87]
	v_mfma_f32_16x16x32_bf16 v[80:83], v[144:147], v[166:169], v[80:83]
	ds_read_b128 v[120:123], v117 offset:4096
	ds_read_b128 v[158:161], v117 offset:5120
	ds_read_b128 v[162:165], v117 offset:6144
	ds_read_b128 v[166:169], v117 offset:7168
	s_waitcnt lgkmcnt(0)
	v_bfe_u32 v117, v138, 5, 1
	v_mfma_f32_16x16x32_bf16 v[60:63], v[130:133], v[120:123], v[60:63]
	s_barrier
	v_mfma_f32_16x16x32_bf16 v[56:59], v[134:137], v[120:123], v[56:59]
	v_mfma_f32_16x16x32_bf16 v[52:55], v[140:143], v[120:123], v[52:55]
	v_mfma_f32_16x16x32_bf16 v[48:51], v[144:147], v[120:123], v[48:51]
	v_lshrrev_b32_e32 v121, 1, v138
	v_lshlrev_b32_e32 v120, 7, v116
	v_and_b32_e32 v121, 8, v121
	v_or3_b32 v122, s15, v120, v121
	v_and_b32_e32 v121, 64, v172
	v_xor_b32_e32 v120, 16, v172
	v_add_u32_e32 v121, 64, v121
	v_cmp_lt_i32_e32 vcc, v120, v121
	v_xor_b32_e32 v123, 32, v172
	v_mfma_f32_16x16x32_bf16 v[76:79], v[130:133], v[174:177], v[76:79]
	v_cndmask_b32_e32 v120, v172, v120, vcc
	v_cmp_lt_i32_e32 vcc, v123, v121
	v_lshlrev_b32_e32 v120, 2, v120
	v_mfma_f32_16x16x32_bf16 v[44:47], v[130:133], v[158:161], v[44:47]
	v_cndmask_b32_e32 v121, v172, v123, vcc
	v_bitop3_b32 v123, v117, v138, 7 bitop3:0x78
	v_lshlrev_b32_e32 v123, 4, v123
	v_or_b32_e32 v126, v122, v123
	s_waitcnt vmcnt(0)
	ds_write_b64 v126, v[124:125]
	v_mul_f32_e32 v124, v179, v179
	v_fmac_f32_e32 v124, v178, v178
	v_fmac_f32_e32 v124, v180, v180
	v_bitop3_b32 v125, v117, v119, 2 bitop3:0x36
	v_fmac_f32_e32 v124, v181, v181
	v_lshlrev_b32_e32 v125, 4, v125
	v_add_f32_e32 v124, v128, v124
	v_cvt_pk_bf16_f32 v126, v178, v179
	v_or_b32_e32 v128, v122, v125
	ds_write_b64 v128, v[126:127]
	v_mul_f32_e32 v126, v183, v183
	v_fmac_f32_e32 v126, v182, v182
	v_fmac_f32_e32 v126, v184, v184
	v_fmac_f32_e32 v126, v185, v185
	v_add_f32_e32 v128, v124, v126
	v_bitop3_b32 v124, v117, v119, 4 bitop3:0x36
	v_lshlrev_b32_e32 v124, 4, v124
	v_mfma_f32_16x16x32_bf16 v[28:31], v[130:133], v[162:165], v[28:31]
	v_cvt_pk_bf16_f32 v126, v182, v183
	v_cvt_pk_bf16_f32 v127, v184, v185
	v_lshlrev_b32_e32 v121, 2, v121
	v_mfma_f32_16x16x32_bf16 v[12:15], v[130:133], v[166:169], v[12:15]
	v_or_b32_e32 v130, v122, v124
	ds_write_b64 v130, v[126:127]
	v_mul_f32_e32 v126, v113, v113
	v_fmac_f32_e32 v126, v112, v112
	v_fmac_f32_e32 v126, v114, v114
	v_fmac_f32_e32 v126, v115, v115
	v_add_f32_e32 v128, v128, v126
	v_cvt_pk_bf16_f32 v126, v112, v113
	v_bitop3_b32 v112, v117, v119, 6 bitop3:0x36
	v_lshlrev_b32_e32 v112, 4, v112
	v_cvt_pk_bf16_f32 v127, v114, v115
	v_or_b32_e32 v113, v122, v112
	ds_write_b64 v113, v[126:127]
	ds_bpermute_b32 v113, v120, v128
	v_mfma_f32_16x16x32_bf16 v[72:75], v[134:137], v[174:177], v[72:75]
	v_cmp_gt_u32_e32 vcc, 16, v118
	v_or_b32_e32 v116, s8, v116
	s_waitcnt lgkmcnt(0)
	v_add_f32_e32 v113, v128, v113
	ds_bpermute_b32 v114, v121, v113
	v_mfma_f32_16x16x32_bf16 v[68:71], v[140:143], v[174:177], v[68:71]
	v_mfma_f32_16x16x32_bf16 v[64:67], v[144:147], v[174:177], v[64:67]
	v_mfma_f32_16x16x32_bf16 v[40:43], v[134:137], v[158:161], v[40:43]
	v_mfma_f32_16x16x32_bf16 v[36:39], v[140:143], v[158:161], v[36:39]
	v_mfma_f32_16x16x32_bf16 v[32:35], v[144:147], v[158:161], v[32:35]
	v_mfma_f32_16x16x32_bf16 v[24:27], v[134:137], v[162:165], v[24:27]
	v_mfma_f32_16x16x32_bf16 v[20:23], v[140:143], v[162:165], v[20:23]
	v_mfma_f32_16x16x32_bf16 v[16:19], v[144:147], v[162:165], v[16:19]
	v_mfma_f32_16x16x32_bf16 v[8:11], v[134:137], v[166:169], v[8:11]
	v_mfma_f32_16x16x32_bf16 v[4:7], v[140:143], v[166:169], v[4:7]
	v_mfma_f32_16x16x32_bf16 v[0:3], v[144:147], v[166:169], v[0:3]
	s_and_saveexec_b64 s[6:7], vcc
	s_cbranch_execz .LBB0_1078
	v_ashrrev_i32_e32 v117, 31, v116
	s_waitcnt lgkmcnt(0)
	v_add_f32_e32 v113, v113, v114
	v_lshlrev_b64 v[114:115], 6, v[116:117]
	v_lshl_add_u64 v[114:115], s[64:65], 0, v[114:115]
	v_lshl_add_u64 v[114:115], s[10:11], 2, v[114:115]
	global_store_dword v[114:115], v113, off
